# GEMM unit start: the second (redundant) zeroing of the 128 accumulators removed at all 12 gemm_phase sites
# speedup vs baseline: 1.0100x; 1.0065x over previous
; #define PG8_STAGE(bufoff, gbase, voff) do { _Pragma("unroll") for (int _i = 0; _i < 2; ++_i) \
;         __builtin_amdgcn_global_load_lds((const unsigned*)((const char*)(gbase) + (voff)[_i]), (LAS unsigned*)(lds + (bufoff) + ldsw + _i * 8192), 16, 0, 0); } while (0)
; #define PG8_WAIT_V(n) asm volatile("s_waitcnt vmcnt(" #n ")" ::: "memory")
; #define PG8_BAR __builtin_amdgcn_s_barrier()
; template <class Epi>
; __device__ __forceinline__ void gemm_phase(LAS unsigned char* lds, const Gemm g, const StaticOrder& S, const Epi& E) {
;     ...
;     f32x4 acc[2][2][4][2];
; #pragma unroll
;     for (int a = 0; a < 2; ++a)
; #pragma unroll
;         for (int b = 0; b < 2; ++b)
; #pragma unroll
;             for (int m = 0; m < 4; ++m)
; #pragma unroll
;                 for (int n = 0; n < 2; ++n) acc[a][b][m][n] = (f32x4){0.f, 0.f, 0.f, 0.f};
;     bf16x8 At[4][2], B0[2][2], B1[2][2];
;     const char* cA = (const char*)g.A + (size_t)cur.pm * tstepA + (size_t)cur.pn * g.a_pn_off * 2; const char* cB = (const char*)g.Bt + (size_t)cur.pn * tstepB;
;     PG8_STAGE(PG8_SB(0, 0), cB, voffB); PG8_STAGE(PG8_SA(0, 0), cA, voffA); PG8_STAGE(PG8_SB(0, 1), cB + hstepB, voffB); PG8_STAGE(PG8_SA(0, 1), cA + hstepA, voffA);
;     if (wr == 1) PG8_BAR;
;     PG8_WAIT_V(4); PG8_BAR;
;     PG8_STAGE(PG8_SB(1, 0), cB + kstep, voffB); PG8_STAGE(PG8_SA(1, 0), cA + kstep, voffA); PG8_STAGE(PG8_SB(1, 1), cB + hstepB + kstep, voffB);
;     PG8_WAIT_V(6); PG8_BAR;
;     for (;;) {
;         const bool has_next = S.next(ui + 1, nxt);
;         const char* nA = has_next ? (const char*)g.A + (size_t)nxt.pm * tstepA + (size_t)nxt.pn * g.a_pn_off * 2 : cA; const char* nB = has_next ? (const char*)g.Bt + (size_t)nxt.pn * tstepB : cB;
;         for (int t = 0; t < nt; t += 2) {
;             const bool last = (t == nt - 2);
;             const char* a1 = cA + (size_t)(t + 1) * kstep;
;             const char* a2 = last ? nA : cA + (size_t)(t + 2) * kstep; const char* b2 = last ? nB : cB + (size_t)(t + 2) * kstep;
.LBB0_1440:
	s_ashr_i32 s29, s28, 31
	s_lshl_b64 s[30:31], s[28:29], 19
	s_add_u32 s29, s74, s30
	s_addc_u32 s34, s75, s31
	s_ashr_i32 s27, s26, 31
	s_lshl_b64 s[30:31], s[26:27], 9
	s_add_u32 s30, s29, s30
	s_addc_u32 s31, s34, s31
	s_lshl_b64 s[34:35], s[26:27], 17
	s_add_u32 s34, s54, s34
	v_mov_b32_e32 v123, 0
	v_cmp_lt_i64_e64 s[10:11], s[10:11], v[188:189]
	s_addc_u32 s35, s55, s35
	s_andn2_b64 vcc, exec, s[24:25]
	v_mov_b32_e32 v122, v123
	v_mov_b32_e32 v121, v123
	v_mov_b32_e32 v120, v123
	v_mov_b32_e32 v127, v123
	v_mov_b32_e32 v126, v123
	v_mov_b32_e32 v125, v123
	v_mov_b32_e32 v124, v123
	v_mov_b32_e32 v111, v123
	v_mov_b32_e32 v110, v123
	v_mov_b32_e32 v109, v123
	v_mov_b32_e32 v108, v123
	v_mov_b32_e32 v107, v123
	v_mov_b32_e32 v106, v123
	v_mov_b32_e32 v105, v123
	v_mov_b32_e32 v104, v123
	v_mov_b32_e32 v95, v123
	v_mov_b32_e32 v94, v123
	v_mov_b32_e32 v93, v123
	v_mov_b32_e32 v92, v123
	v_mov_b32_e32 v91, v123
	v_mov_b32_e32 v90, v123
	v_mov_b32_e32 v89, v123
	v_mov_b32_e32 v88, v123
	v_mov_b32_e32 v79, v123
	v_mov_b32_e32 v78, v123
	v_mov_b32_e32 v77, v123
	v_mov_b32_e32 v76, v123
	v_mov_b32_e32 v75, v123
	v_mov_b32_e32 v74, v123
	v_mov_b32_e32 v73, v123
	v_mov_b32_e32 v72, v123
	v_mov_b32_e32 v119, v123
	v_mov_b32_e32 v118, v123
	v_mov_b32_e32 v117, v123
	v_mov_b32_e32 v116, v123
	v_mov_b32_e32 v115, v123
	v_mov_b32_e32 v114, v123
	v_mov_b32_e32 v113, v123
	v_mov_b32_e32 v112, v123
	v_mov_b32_e32 v103, v123
	v_mov_b32_e32 v102, v123
	v_mov_b32_e32 v101, v123
	v_mov_b32_e32 v100, v123
	v_mov_b32_e32 v99, v123
	v_mov_b32_e32 v98, v123
	v_mov_b32_e32 v97, v123
	v_mov_b32_e32 v96, v123
	v_mov_b32_e32 v87, v123
	v_mov_b32_e32 v86, v123
	v_mov_b32_e32 v85, v123
	v_mov_b32_e32 v84, v123
	v_mov_b32_e32 v83, v123
	v_mov_b32_e32 v82, v123
	v_mov_b32_e32 v81, v123
	v_mov_b32_e32 v80, v123
	v_mov_b32_e32 v71, v123
	v_mov_b32_e32 v70, v123
	v_mov_b32_e32 v69, v123
	v_mov_b32_e32 v68, v123
	v_mov_b32_e32 v67, v123
	v_mov_b32_e32 v66, v123
	v_mov_b32_e32 v65, v123
	v_mov_b32_e32 v64, v123
	v_mov_b32_e32 v63, v123
	v_mov_b32_e32 v62, v123
	v_mov_b32_e32 v61, v123
	v_mov_b32_e32 v60, v123
	v_mov_b32_e32 v59, v123
	v_mov_b32_e32 v58, v123
	v_mov_b32_e32 v57, v123
	v_mov_b32_e32 v56, v123
	v_mov_b32_e32 v47, v123
	v_mov_b32_e32 v46, v123
	v_mov_b32_e32 v45, v123
	v_mov_b32_e32 v44, v123
	v_mov_b32_e32 v43, v123
	v_mov_b32_e32 v42, v123
	v_mov_b32_e32 v41, v123
	v_mov_b32_e32 v40, v123
	s_waitcnt vmcnt(0)
	v_mov_b32_e32 v31, v123
	v_mov_b32_e32 v30, v123
	v_mov_b32_e32 v29, v123
	v_mov_b32_e32 v28, v123
	v_mov_b32_e32 v27, v123
	v_mov_b32_e32 v26, v123
	v_mov_b32_e32 v25, v123
	v_mov_b32_e32 v24, v123
	v_mov_b32_e32 v15, v123
	v_mov_b32_e32 v14, v123
	v_mov_b32_e32 v13, v123
	v_mov_b32_e32 v12, v123
	v_mov_b32_e32 v11, v123
	v_mov_b32_e32 v10, v123
	v_mov_b32_e32 v9, v123
	v_mov_b32_e32 v8, v123
	v_mov_b32_e32 v55, v123
	v_mov_b32_e32 v54, v123
	v_mov_b32_e32 v53, v123
	v_mov_b32_e32 v52, v123
	v_mov_b32_e32 v51, v123
	v_mov_b32_e32 v50, v123
	v_mov_b32_e32 v49, v123
	v_mov_b32_e32 v48, v123
	v_mov_b32_e32 v39, v123
	v_mov_b32_e32 v38, v123
	v_mov_b32_e32 v37, v123
	v_mov_b32_e32 v36, v123
	v_mov_b32_e32 v35, v123
	v_mov_b32_e32 v34, v123
	v_mov_b32_e32 v33, v123
	v_mov_b32_e32 v32, v123
	v_mov_b32_e32 v23, v123
	v_mov_b32_e32 v22, v123
	v_mov_b32_e32 v21, v123
	v_mov_b32_e32 v20, v123
	v_mov_b32_e32 v19, v123
	v_mov_b32_e32 v18, v123
	v_mov_b32_e32 v17, v123
	v_mov_b32_e32 v16, v123
	v_mov_b32_e32 v7, v123
	v_mov_b32_e32 v6, v123
	v_mov_b32_e32 v5, v123
	v_mov_b32_e32 v4, v123
	v_mov_b32_e32 v3, v123
	v_mov_b32_e32 v2, v123
	s_waitcnt lgkmcnt(0)
	v_mov_b32_e32 v1, v123
	v_mov_b32_e32 v0, v123
	s_cbranch_vccnz .LBB0_1443
	s_and_b64 s[10:11], s[10:11], exec
	s_cselect_b32 s27, s31, s43
	s_cselect_b32 s29, s30, s42
	s_cselect_b32 s64, s35, s41
	s_cselect_b32 s65, s34, s40
	s_add_u32 s10, s42, 0x40080
	s_addc_u32 s11, s43, 0
	s_add_u32 s80, s40, 0x100
	s_addc_u32 s81, s41, 0
	s_mov_b32 s40, 0

; #define PG8_STAGE(bufoff, gbase, voff) do { _Pragma("unroll") for (int _i = 0; _i < 2; ++_i) \
;         __builtin_amdgcn_global_load_lds((const unsigned*)((const char*)(gbase) + (voff)[_i]), (LAS unsigned*)(lds + (bufoff) + ldsw + _i * 8192), 16, 0, 0); } while (0)
; #define PG8_WAIT_V(n) asm volatile("s_waitcnt vmcnt(" #n ")" ::: "memory")
; #define PG8_BAR __builtin_amdgcn_s_barrier()
; template <class Epi>
; __device__ __forceinline__ void gemm_phase(LAS unsigned char* lds, const Gemm g, const StaticOrder& S, const Epi& E) {
;     ...
;     f32x4 acc[2][2][4][2];
; #pragma unroll
;     for (int a = 0; a < 2; ++a)
; #pragma unroll
;         for (int b = 0; b < 2; ++b)
; #pragma unroll
;             for (int m = 0; m < 4; ++m)
; #pragma unroll
;                 for (int n = 0; n < 2; ++n) acc[a][b][m][n] = (f32x4){0.f, 0.f, 0.f, 0.f};
;     bf16x8 At[4][2], B0[2][2], B1[2][2];
;     const char* cA = (const char*)g.A + (size_t)cur.pm * tstepA + (size_t)cur.pn * g.a_pn_off * 2; const char* cB = (const char*)g.Bt + (size_t)cur.pn * tstepB;
;     PG8_STAGE(PG8_SB(0, 0), cB, voffB); PG8_STAGE(PG8_SA(0, 0), cA, voffA); PG8_STAGE(PG8_SB(0, 1), cB + hstepB, voffB); PG8_STAGE(PG8_SA(0, 1), cA + hstepA, voffA);
;     if (wr == 1) PG8_BAR;
;     PG8_WAIT_V(4); PG8_BAR;
;     PG8_STAGE(PG8_SB(1, 0), cB + kstep, voffB); PG8_STAGE(PG8_SA(1, 0), cA + kstep, voffA); PG8_STAGE(PG8_SB(1, 1), cB + hstepB + kstep, voffB);
;     PG8_WAIT_V(6); PG8_BAR;
;     for (;;) {
;         const bool has_next = S.next(ui + 1, nxt);
;         const char* nA = has_next ? (const char*)g.A + (size_t)nxt.pm * tstepA + (size_t)nxt.pn * g.a_pn_off * 2 : cA; const char* nB = has_next ? (const char*)g.Bt + (size_t)nxt.pn * tstepB : cB;
;         for (int t = 0; t < nt; t += 2) {
;             const bool last = (t == nt - 2);
;             const char* a1 = cA + (size_t)(t + 1) * kstep;
;             const char* a2 = last ? nA : cA + (size_t)(t + 2) * kstep; const char* b2 = last ? nB : cB + (size_t)(t + 2) * kstep;
.LBB0_1542:
	s_ashr_i32 s17, s16, 31
	s_lshl_b64 s[18:19], s[16:17], 19
	s_add_u32 s18, s70, s18
	s_addc_u32 s19, s71, s19
	s_ashr_i32 s15, s14, 31
	s_lshl_b64 s[22:23], s[14:15], 19
	s_add_u32 s22, s31, s22
	v_mov_b32_e32 v119, 0
	v_cmp_lt_i64_e64 s[8:9], s[8:9], v[140:141]
	s_addc_u32 s23, s34, s23
	s_andn2_b64 vcc, exec, s[12:13]
	v_mov_b32_e32 v118, v119
	v_mov_b32_e32 v117, v119
	v_mov_b32_e32 v116, v119
	v_mov_b32_e32 v115, v119
	v_mov_b32_e32 v114, v119
	v_mov_b32_e32 v113, v119
	v_mov_b32_e32 v112, v119
	v_mov_b32_e32 v107, v119
	v_mov_b32_e32 v106, v119
	v_mov_b32_e32 v105, v119
	v_mov_b32_e32 v104, v119
	v_mov_b32_e32 v99, v119
	v_mov_b32_e32 v98, v119
	v_mov_b32_e32 v97, v119
	v_mov_b32_e32 v96, v119
	v_mov_b32_e32 v91, v119
	v_mov_b32_e32 v90, v119
	v_mov_b32_e32 v89, v119
	v_mov_b32_e32 v88, v119
	v_mov_b32_e32 v83, v119
	v_mov_b32_e32 v82, v119
	v_mov_b32_e32 v81, v119
	v_mov_b32_e32 v80, v119
	v_mov_b32_e32 v75, v119
	v_mov_b32_e32 v74, v119
	v_mov_b32_e32 v73, v119
	v_mov_b32_e32 v72, v119
	v_mov_b32_e32 v67, v119
	v_mov_b32_e32 v66, v119
	v_mov_b32_e32 v65, v119
	v_mov_b32_e32 v64, v119
	v_mov_b32_e32 v127, v119
	v_mov_b32_e32 v126, v119
	v_mov_b32_e32 v125, v119
	v_mov_b32_e32 v124, v119
	v_mov_b32_e32 v123, v119
	v_mov_b32_e32 v122, v119
	v_mov_b32_e32 v121, v119
	v_mov_b32_e32 v120, v119
	v_mov_b32_e32 v111, v119
	v_mov_b32_e32 v110, v119
	v_mov_b32_e32 v109, v119
	v_mov_b32_e32 v108, v119
	v_mov_b32_e32 v103, v119
	v_mov_b32_e32 v102, v119
	v_mov_b32_e32 v101, v119
	v_mov_b32_e32 v100, v119
	v_mov_b32_e32 v95, v119
	v_mov_b32_e32 v94, v119
	v_mov_b32_e32 v93, v119
	v_mov_b32_e32 v92, v119
	v_mov_b32_e32 v87, v119
	v_mov_b32_e32 v86, v119
	v_mov_b32_e32 v85, v119
	v_mov_b32_e32 v84, v119
	v_mov_b32_e32 v79, v119
	v_mov_b32_e32 v78, v119
	v_mov_b32_e32 v77, v119
	v_mov_b32_e32 v76, v119
	v_mov_b32_e32 v71, v119
	v_mov_b32_e32 v70, v119
	v_mov_b32_e32 v69, v119
	v_mov_b32_e32 v68, v119
	v_mov_b32_e32 v59, v119
	v_mov_b32_e32 v58, v119
	v_mov_b32_e32 v57, v119
	v_mov_b32_e32 v56, v119
	v_mov_b32_e32 v51, v119
	v_mov_b32_e32 v50, v119
	v_mov_b32_e32 v49, v119
	v_mov_b32_e32 v48, v119
	v_mov_b32_e32 v43, v119
	v_mov_b32_e32 v42, v119
	v_mov_b32_e32 v41, v119
	v_mov_b32_e32 v40, v119
	v_mov_b32_e32 v35, v119
	v_mov_b32_e32 v34, v119
	v_mov_b32_e32 v33, v119
	v_mov_b32_e32 v32, v119
	v_mov_b32_e32 v27, v119
	v_mov_b32_e32 v26, v119
	v_mov_b32_e32 v25, v119
	v_mov_b32_e32 v24, v119
	v_mov_b32_e32 v19, v119
	v_mov_b32_e32 v18, v119
	v_mov_b32_e32 v17, v119
	v_mov_b32_e32 v16, v119
	v_mov_b32_e32 v11, v119
	v_mov_b32_e32 v10, v119
	v_mov_b32_e32 v9, v119
	v_mov_b32_e32 v8, v119
	v_mov_b32_e32 v7, v119
	v_mov_b32_e32 v6, v119
	v_mov_b32_e32 v5, v119
	v_mov_b32_e32 v4, v119
	v_mov_b32_e32 v63, v119
	v_mov_b32_e32 v62, v119
	v_mov_b32_e32 v61, v119
	v_mov_b32_e32 v60, v119
	v_mov_b32_e32 v55, v119
	v_mov_b32_e32 v54, v119
	v_mov_b32_e32 v53, v119
	v_mov_b32_e32 v52, v119
	v_mov_b32_e32 v47, v119
	v_mov_b32_e32 v46, v119
	v_mov_b32_e32 v45, v119
	v_mov_b32_e32 v44, v119
	s_waitcnt vmcnt(0)
	v_mov_b32_e32 v39, v119
	v_mov_b32_e32 v38, v119
	v_mov_b32_e32 v37, v119
	v_mov_b32_e32 v36, v119
	v_mov_b32_e32 v31, v119
	v_mov_b32_e32 v30, v119
	v_mov_b32_e32 v29, v119
	v_mov_b32_e32 v28, v119
	v_mov_b32_e32 v23, v119
	v_mov_b32_e32 v22, v119
	v_mov_b32_e32 v21, v119
	v_mov_b32_e32 v20, v119
	v_mov_b32_e32 v15, v119
	v_mov_b32_e32 v14, v119
	v_mov_b32_e32 v13, v119
	v_mov_b32_e32 v12, v119
	v_mov_b32_e32 v3, v119
	v_mov_b32_e32 v2, v119
	v_mov_b32_e32 v1, v119
	v_mov_b32_e32 v0, v119
	s_cbranch_vccnz .LBB0_1535
	s_and_b64 s[8:9], s[8:9], exec
	s_cselect_b32 s15, s19, s29
	s_cselect_b32 s17, s18, s28
	s_cselect_b32 s63, s23, s27
	s_cselect_b32 s64, s22, s26
	s_add_u32 s8, s28, 0x40080
	s_addc_u32 s9, s29, 0
	s_add_u32 s65, s26, 0x100
	s_addc_u32 s76, s27, 0
	s_mov_b32 s26, 0

; #define PG8_STAGE(bufoff, gbase, voff) do { _Pragma("unroll") for (int _i = 0; _i < 2; ++_i) \
;         __builtin_amdgcn_global_load_lds((const unsigned*)((const char*)(gbase) + (voff)[_i]), (LAS unsigned*)(lds + (bufoff) + ldsw + _i * 8192), 16, 0, 0); } while (0)
; #define PG8_WAIT_V(n) asm volatile("s_waitcnt vmcnt(" #n ")" ::: "memory")
; #define PG8_BAR __builtin_amdgcn_s_barrier()
; template <class Epi>
; __device__ __forceinline__ void gemm_phase(LAS unsigned char* lds, const Gemm g, const StaticOrder& S, const Epi& E) {
;     ...
;     f32x4 acc[2][2][4][2];
; #pragma unroll
;     for (int a = 0; a < 2; ++a)
; #pragma unroll
;         for (int b = 0; b < 2; ++b)
; #pragma unroll
;             for (int m = 0; m < 4; ++m)
; #pragma unroll
;                 for (int n = 0; n < 2; ++n) acc[a][b][m][n] = (f32x4){0.f, 0.f, 0.f, 0.f};
;     bf16x8 At[4][2], B0[2][2], B1[2][2];
;     const char* cA = (const char*)g.A + (size_t)cur.pm * tstepA + (size_t)cur.pn * g.a_pn_off * 2; const char* cB = (const char*)g.Bt + (size_t)cur.pn * tstepB;
;     PG8_STAGE(PG8_SB(0, 0), cB, voffB); PG8_STAGE(PG8_SA(0, 0), cA, voffA); PG8_STAGE(PG8_SB(0, 1), cB + hstepB, voffB); PG8_STAGE(PG8_SA(0, 1), cA + hstepA, voffA);
;     if (wr == 1) PG8_BAR;
;     PG8_WAIT_V(4); PG8_BAR;
;     PG8_STAGE(PG8_SB(1, 0), cB + kstep, voffB); PG8_STAGE(PG8_SA(1, 0), cA + kstep, voffA); PG8_STAGE(PG8_SB(1, 1), cB + hstepB + kstep, voffB);
;     PG8_WAIT_V(6); PG8_BAR;
;     for (;;) {
;         const bool has_next = S.next(ui + 1, nxt);
;         const char* nA = has_next ? (const char*)g.A + (size_t)nxt.pm * tstepA + (size_t)nxt.pn * g.a_pn_off * 2 : cA; const char* nB = has_next ? (const char*)g.Bt + (size_t)nxt.pn * tstepB : cB;
;         for (int t = 0; t < nt; t += 2) {
;             const bool last = (t == nt - 2);
;             const char* a1 = cA + (size_t)(t + 1) * kstep;
;             const char* a2 = last ? nA : cA + (size_t)(t + 2) * kstep; const char* b2 = last ? nB : cB + (size_t)(t + 2) * kstep;
.LBB0_1564:
	s_ashr_i32 s21, s20, 31
	s_lshl_b64 s[22:23], s[20:21], 17
	s_add_u32 s22, s68, s22
	s_addc_u32 s23, s69, s23
	s_ashr_i32 s19, s18, 31
	s_lshl_b64 s[24:25], s[18:19], 17
	s_add_u32 s24, s12, s24
	v_mov_b32_e32 v127, 0
	v_cmp_lt_i64_e64 s[10:11], s[10:11], v[140:141]
	s_addc_u32 s25, s13, s25
	s_and_b64 vcc, exec, s[6:7]
	v_mov_b32_e32 v126, v127
	v_mov_b32_e32 v125, v127
	v_mov_b32_e32 v124, v127
	v_mov_b32_e32 v123, v127
	v_mov_b32_e32 v122, v127
	v_mov_b32_e32 v121, v127
	v_mov_b32_e32 v120, v127
	v_mov_b32_e32 v111, v127
	v_mov_b32_e32 v110, v127
	v_mov_b32_e32 v109, v127
	v_mov_b32_e32 v108, v127
	v_mov_b32_e32 v107, v127
	v_mov_b32_e32 v106, v127
	v_mov_b32_e32 v105, v127
	v_mov_b32_e32 v104, v127
	v_mov_b32_e32 v95, v127
	v_mov_b32_e32 v94, v127
	v_mov_b32_e32 v93, v127
	v_mov_b32_e32 v92, v127
	v_mov_b32_e32 v91, v127
	v_mov_b32_e32 v90, v127
	v_mov_b32_e32 v89, v127
	v_mov_b32_e32 v88, v127
	v_mov_b32_e32 v79, v127
	v_mov_b32_e32 v78, v127
	v_mov_b32_e32 v77, v127
	v_mov_b32_e32 v76, v127
	v_mov_b32_e32 v75, v127
	v_mov_b32_e32 v74, v127
	v_mov_b32_e32 v73, v127
	v_mov_b32_e32 v72, v127
	v_mov_b32_e32 v119, v127
	v_mov_b32_e32 v118, v127
	v_mov_b32_e32 v117, v127
	v_mov_b32_e32 v116, v127
	v_mov_b32_e32 v115, v127
	v_mov_b32_e32 v114, v127
	v_mov_b32_e32 v113, v127
	v_mov_b32_e32 v112, v127
	v_mov_b32_e32 v103, v127
	v_mov_b32_e32 v102, v127
	v_mov_b32_e32 v101, v127
	v_mov_b32_e32 v100, v127
	v_mov_b32_e32 v99, v127
	v_mov_b32_e32 v98, v127
	v_mov_b32_e32 v97, v127
	v_mov_b32_e32 v96, v127
	v_mov_b32_e32 v87, v127
	v_mov_b32_e32 v86, v127
	v_mov_b32_e32 v85, v127
	v_mov_b32_e32 v84, v127
	v_mov_b32_e32 v83, v127
	v_mov_b32_e32 v82, v127
	v_mov_b32_e32 v81, v127
	v_mov_b32_e32 v80, v127
	v_mov_b32_e32 v71, v127
	v_mov_b32_e32 v70, v127
	v_mov_b32_e32 v69, v127
	v_mov_b32_e32 v68, v127
	v_mov_b32_e32 v67, v127
	v_mov_b32_e32 v66, v127
	v_mov_b32_e32 v65, v127
	v_mov_b32_e32 v64, v127
	v_mov_b32_e32 v63, v127
	v_mov_b32_e32 v62, v127
	v_mov_b32_e32 v61, v127
	v_mov_b32_e32 v60, v127
	v_mov_b32_e32 v59, v127
	v_mov_b32_e32 v58, v127
	v_mov_b32_e32 v57, v127
	v_mov_b32_e32 v56, v127
	v_mov_b32_e32 v47, v127
	v_mov_b32_e32 v46, v127
	v_mov_b32_e32 v45, v127
	v_mov_b32_e32 v44, v127
	v_mov_b32_e32 v43, v127
	v_mov_b32_e32 v42, v127
	v_mov_b32_e32 v41, v127
	v_mov_b32_e32 v40, v127
	v_mov_b32_e32 v31, v127
	v_mov_b32_e32 v30, v127
	v_mov_b32_e32 v29, v127
	v_mov_b32_e32 v28, v127
	v_mov_b32_e32 v27, v127
	v_mov_b32_e32 v26, v127
	v_mov_b32_e32 v25, v127
	v_mov_b32_e32 v24, v127
	v_mov_b32_e32 v15, v127
	v_mov_b32_e32 v14, v127
	v_mov_b32_e32 v13, v127
	v_mov_b32_e32 v12, v127
	v_mov_b32_e32 v11, v127
	v_mov_b32_e32 v10, v127
	v_mov_b32_e32 v9, v127
	v_mov_b32_e32 v8, v127
	v_mov_b32_e32 v55, v127
	v_mov_b32_e32 v54, v127
	v_mov_b32_e32 v53, v127
	v_mov_b32_e32 v52, v127
	v_mov_b32_e32 v51, v127
	v_mov_b32_e32 v50, v127
	v_mov_b32_e32 v49, v127
	v_mov_b32_e32 v48, v127
	v_mov_b32_e32 v39, v127
	v_mov_b32_e32 v38, v127
	v_mov_b32_e32 v37, v127
	v_mov_b32_e32 v36, v127
	v_mov_b32_e32 v35, v127
	v_mov_b32_e32 v34, v127
	v_mov_b32_e32 v33, v127
	v_mov_b32_e32 v32, v127
	v_mov_b32_e32 v23, v127
	v_mov_b32_e32 v22, v127
	v_mov_b32_e32 v21, v127
	v_mov_b32_e32 v20, v127
	v_mov_b32_e32 v19, v127
	v_mov_b32_e32 v18, v127
	v_mov_b32_e32 v17, v127
	v_mov_b32_e32 v16, v127
	v_mov_b32_e32 v7, v127
	v_mov_b32_e32 v6, v127
	v_mov_b32_e32 v5, v127
	v_mov_b32_e32 v4, v127
	v_mov_b32_e32 v3, v127
	v_mov_b32_e32 v2, v127
	v_mov_b32_e32 v1, v127
	v_mov_b32_e32 v0, v127
	s_cbranch_vccnz .LBB0_1557
	s_and_b64 s[10:11], s[10:11], exec
	s_cselect_b32 s19, s23, s29
	s_cselect_b32 s21, s22, s28
	s_cselect_b32 s60, s25, s27
	s_cselect_b32 s61, s24, s26
	s_add_u32 s10, s28, 0x10080
	s_addc_u32 s11, s29, 0
	s_add_u32 s62, s26, 0x100
	s_addc_u32 s63, s27, 0
	s_mov_b32 s26, 0

; #define PG8_STAGE(bufoff, gbase, voff) do { _Pragma("unroll") for (int _i = 0; _i < 2; ++_i) \
;         __builtin_amdgcn_global_load_lds((const unsigned*)((const char*)(gbase) + (voff)[_i]), (LAS unsigned*)(lds + (bufoff) + ldsw + _i * 8192), 16, 0, 0); } while (0)
; #define PG8_WAIT_V(n) asm volatile("s_waitcnt vmcnt(" #n ")" ::: "memory")
; #define PG8_BAR __builtin_amdgcn_s_barrier()
; template <class Epi>
; __device__ __forceinline__ void gemm_phase(LAS unsigned char* lds, const Gemm g, const StaticOrder& S, const Epi& E) {
;     ...
;     f32x4 acc[2][2][4][2];
; #pragma unroll
;     for (int a = 0; a < 2; ++a)
; #pragma unroll
;         for (int b = 0; b < 2; ++b)
; #pragma unroll
;             for (int m = 0; m < 4; ++m)
; #pragma unroll
;                 for (int n = 0; n < 2; ++n) acc[a][b][m][n] = (f32x4){0.f, 0.f, 0.f, 0.f};
;     bf16x8 At[4][2], B0[2][2], B1[2][2];
;     const char* cA = (const char*)g.A + (size_t)cur.pm * tstepA + (size_t)cur.pn * g.a_pn_off * 2; const char* cB = (const char*)g.Bt + (size_t)cur.pn * tstepB;
;     PG8_STAGE(PG8_SB(0, 0), cB, voffB); PG8_STAGE(PG8_SA(0, 0), cA, voffA); PG8_STAGE(PG8_SB(0, 1), cB + hstepB, voffB); PG8_STAGE(PG8_SA(0, 1), cA + hstepA, voffA);
;     if (wr == 1) PG8_BAR;
;     PG8_WAIT_V(4); PG8_BAR;
;     PG8_STAGE(PG8_SB(1, 0), cB + kstep, voffB); PG8_STAGE(PG8_SA(1, 0), cA + kstep, voffA); PG8_STAGE(PG8_SB(1, 1), cB + hstepB + kstep, voffB);
;     PG8_WAIT_V(6); PG8_BAR;
;     for (;;) {
;         const bool has_next = S.next(ui + 1, nxt);
;         const char* nA = has_next ? (const char*)g.A + (size_t)nxt.pm * tstepA + (size_t)nxt.pn * g.a_pn_off * 2 : cA; const char* nB = has_next ? (const char*)g.Bt + (size_t)nxt.pn * tstepB : cB;
;         for (int t = 0; t < nt; t += 2) {
.LBB0_1651:
	v_mov_b32_e32 v119, 0
	s_andn2_b64 vcc, exec, s[20:21]
	v_mov_b32_e32 v118, v119
	v_mov_b32_e32 v117, v119
	v_mov_b32_e32 v116, v119
	v_mov_b32_e32 v127, v119
	v_mov_b32_e32 v126, v119
	v_mov_b32_e32 v125, v119
	v_mov_b32_e32 v124, v119
	v_mov_b32_e32 v111, v119
	v_mov_b32_e32 v110, v119
	v_mov_b32_e32 v109, v119
	v_mov_b32_e32 v108, v119
	v_mov_b32_e32 v107, v119
	v_mov_b32_e32 v106, v119
	v_mov_b32_e32 v105, v119
	v_mov_b32_e32 v104, v119
	v_mov_b32_e32 v95, v119
	v_mov_b32_e32 v94, v119
	v_mov_b32_e32 v93, v119
	v_mov_b32_e32 v92, v119
	v_mov_b32_e32 v91, v119
	v_mov_b32_e32 v90, v119
	v_mov_b32_e32 v89, v119
	v_mov_b32_e32 v88, v119
	v_mov_b32_e32 v79, v119
	v_mov_b32_e32 v78, v119
	v_mov_b32_e32 v77, v119
	v_mov_b32_e32 v76, v119
	v_mov_b32_e32 v75, v119
	v_mov_b32_e32 v74, v119
	v_mov_b32_e32 v73, v119
	v_mov_b32_e32 v72, v119
	v_mov_b32_e32 v123, v119
	v_mov_b32_e32 v122, v119
	v_mov_b32_e32 v121, v119
	v_mov_b32_e32 v120, v119
	v_mov_b32_e32 v115, v119
	v_mov_b32_e32 v114, v119
	v_mov_b32_e32 v113, v119
	v_mov_b32_e32 v112, v119
	v_mov_b32_e32 v103, v119
	v_mov_b32_e32 v102, v119
	v_mov_b32_e32 v101, v119
	v_mov_b32_e32 v100, v119
	v_mov_b32_e32 v99, v119
	v_mov_b32_e32 v98, v119
	v_mov_b32_e32 v97, v119
	v_mov_b32_e32 v96, v119
	v_mov_b32_e32 v87, v119
	v_mov_b32_e32 v86, v119
	v_mov_b32_e32 v85, v119
	v_mov_b32_e32 v84, v119
	v_mov_b32_e32 v83, v119
	v_mov_b32_e32 v82, v119
	v_mov_b32_e32 v81, v119
	v_mov_b32_e32 v80, v119
	v_mov_b32_e32 v71, v119
	v_mov_b32_e32 v70, v119
	v_mov_b32_e32 v69, v119
	v_mov_b32_e32 v68, v119
	v_mov_b32_e32 v67, v119
	v_mov_b32_e32 v66, v119
	v_mov_b32_e32 v65, v119
	v_mov_b32_e32 v64, v119
	v_mov_b32_e32 v63, v119
	v_mov_b32_e32 v62, v119
	v_mov_b32_e32 v61, v119
	v_mov_b32_e32 v60, v119
	v_mov_b32_e32 v59, v119
	v_mov_b32_e32 v58, v119
	v_mov_b32_e32 v57, v119
	v_mov_b32_e32 v56, v119
	v_mov_b32_e32 v47, v119
	v_mov_b32_e32 v46, v119
	v_mov_b32_e32 v45, v119
	v_mov_b32_e32 v44, v119
	v_mov_b32_e32 v43, v119
	v_mov_b32_e32 v42, v119
	v_mov_b32_e32 v41, v119
	v_mov_b32_e32 v40, v119
	v_mov_b32_e32 v31, v119
	v_mov_b32_e32 v30, v119
	v_mov_b32_e32 v29, v119
	v_mov_b32_e32 v28, v119
	v_mov_b32_e32 v27, v119
	v_mov_b32_e32 v26, v119
	v_mov_b32_e32 v25, v119
	v_mov_b32_e32 v24, v119
	v_mov_b32_e32 v15, v119
	v_mov_b32_e32 v14, v119
	v_mov_b32_e32 v13, v119
	v_mov_b32_e32 v12, v119
	v_mov_b32_e32 v11, v119
	v_mov_b32_e32 v10, v119
	v_mov_b32_e32 v9, v119
	v_mov_b32_e32 v8, v119
	v_mov_b32_e32 v55, v119
	v_mov_b32_e32 v54, v119
	v_mov_b32_e32 v53, v119
	v_mov_b32_e32 v52, v119
	v_mov_b32_e32 v51, v119
	v_mov_b32_e32 v50, v119
	v_mov_b32_e32 v49, v119
	v_mov_b32_e32 v48, v119
	v_mov_b32_e32 v39, v119
	v_mov_b32_e32 v38, v119
	v_mov_b32_e32 v37, v119
	v_mov_b32_e32 v36, v119
	v_mov_b32_e32 v35, v119
	v_mov_b32_e32 v34, v119
	v_mov_b32_e32 v33, v119
	v_mov_b32_e32 v32, v119
	v_mov_b32_e32 v23, v119
	v_mov_b32_e32 v22, v119
	v_mov_b32_e32 v21, v119
	v_mov_b32_e32 v20, v119
	v_mov_b32_e32 v19, v119
	v_mov_b32_e32 v18, v119
	v_mov_b32_e32 v17, v119
	v_mov_b32_e32 v16, v119
	v_mov_b32_e32 v7, v119
	v_mov_b32_e32 v6, v119
	v_mov_b32_e32 v5, v119
	v_mov_b32_e32 v4, v119
	v_mov_b32_e32 v3, v119
	v_mov_b32_e32 v2, v119
	s_waitcnt lgkmcnt(0)
	v_mov_b32_e32 v1, v119
	v_mov_b32_e32 v0, v119
	s_cbranch_vccnz .LBB0_1654
	s_add_u32 s63, s26, 0x100
	s_addc_u32 s64, s27, 0
	s_mov_b32 s26, 0

; #define PG8_STAGE(bufoff, gbase, voff) do { _Pragma("unroll") for (int _i = 0; _i < 2; ++_i) \
;         __builtin_amdgcn_global_load_lds((const unsigned*)((const char*)(gbase) + (voff)[_i]), (LAS unsigned*)(lds + (bufoff) + ldsw + _i * 8192), 16, 0, 0); } while (0)
; #define PG8_WAIT_V(n) asm volatile("s_waitcnt vmcnt(" #n ")" ::: "memory")
; #define PG8_BAR __builtin_amdgcn_s_barrier()
; template <class Epi>
; __device__ __forceinline__ void gemm_phase(LAS unsigned char* lds, const Gemm g, const StaticOrder& S, const Epi& E) {
;     ...
;     f32x4 acc[2][2][4][2];
; #pragma unroll
;     for (int a = 0; a < 2; ++a)
; #pragma unroll
;         for (int b = 0; b < 2; ++b)
; #pragma unroll
;             for (int m = 0; m < 4; ++m)
; #pragma unroll
;                 for (int n = 0; n < 2; ++n) acc[a][b][m][n] = (f32x4){0.f, 0.f, 0.f, 0.f};
;     bf16x8 At[4][2], B0[2][2], B1[2][2];
;     const char* cA = (const char*)g.A + (size_t)cur.pm * tstepA + (size_t)cur.pn * g.a_pn_off * 2; const char* cB = (const char*)g.Bt + (size_t)cur.pn * tstepB;
;     PG8_STAGE(PG8_SB(0, 0), cB, voffB); PG8_STAGE(PG8_SA(0, 0), cA, voffA); PG8_STAGE(PG8_SB(0, 1), cB + hstepB, voffB); PG8_STAGE(PG8_SA(0, 1), cA + hstepA, voffA);
;     if (wr == 1) PG8_BAR;
;     PG8_WAIT_V(4); PG8_BAR;
;     PG8_STAGE(PG8_SB(1, 0), cB + kstep, voffB); PG8_STAGE(PG8_SA(1, 0), cA + kstep, voffA); PG8_STAGE(PG8_SB(1, 1), cB + hstepB + kstep, voffB);
;     PG8_WAIT_V(6); PG8_BAR;
;     for (;;) {
;         const bool has_next = S.next(ui + 1, nxt);
;         const char* nA = has_next ? (const char*)g.A + (size_t)nxt.pm * tstepA + (size_t)nxt.pn * g.a_pn_off * 2 : cA; const char* nB = has_next ? (const char*)g.Bt + (size_t)nxt.pn * tstepB : cB;
;         for (int t = 0; t < nt; t += 2) {
;             const bool last = (t == nt - 2);
;             const char* a1 = cA + (size_t)(t + 1) * kstep;
;             const char* a2 = last ? nA : cA + (size_t)(t + 2) * kstep; const char* b2 = last ? nB : cB + (size_t)(t + 2) * kstep;
.LBB0_1751:
	s_ashr_i32 s25, s24, 31
	s_lshl_b64 s[26:27], s[24:25], 19
	s_add_u32 s26, s68, s26
	s_addc_u32 s27, s69, s27
	s_ashr_i32 s23, s22, 31
	s_lshl_b64 s[28:29], s[22:23], 19
	s_add_u32 s28, s18, s28
	v_mov_b32_e32 v127, 0
	v_cmp_lt_i64_e64 s[12:13], s[12:13], v[172:173]
	s_addc_u32 s29, s19, s29
	s_and_b64 vcc, exec, s[8:9]
	v_mov_b32_e32 v126, v127
	v_mov_b32_e32 v125, v127
	v_mov_b32_e32 v124, v127
	v_mov_b32_e32 v123, v127
	v_mov_b32_e32 v122, v127
	v_mov_b32_e32 v121, v127
	v_mov_b32_e32 v120, v127
	v_mov_b32_e32 v111, v127
	v_mov_b32_e32 v110, v127
	v_mov_b32_e32 v109, v127
	v_mov_b32_e32 v108, v127
	v_mov_b32_e32 v107, v127
	v_mov_b32_e32 v106, v127
	v_mov_b32_e32 v105, v127
	v_mov_b32_e32 v104, v127
	v_mov_b32_e32 v95, v127
	v_mov_b32_e32 v94, v127
	v_mov_b32_e32 v93, v127
	v_mov_b32_e32 v92, v127
	v_mov_b32_e32 v91, v127
	v_mov_b32_e32 v90, v127
	v_mov_b32_e32 v89, v127
	v_mov_b32_e32 v88, v127
	v_mov_b32_e32 v79, v127
	v_mov_b32_e32 v78, v127
	v_mov_b32_e32 v77, v127
	v_mov_b32_e32 v76, v127
	v_mov_b32_e32 v75, v127
	v_mov_b32_e32 v74, v127
	v_mov_b32_e32 v73, v127
	v_mov_b32_e32 v72, v127
	v_mov_b32_e32 v119, v127
	v_mov_b32_e32 v118, v127
	v_mov_b32_e32 v117, v127
	v_mov_b32_e32 v116, v127
	v_mov_b32_e32 v115, v127
	v_mov_b32_e32 v114, v127
	v_mov_b32_e32 v113, v127
	v_mov_b32_e32 v112, v127
	v_mov_b32_e32 v103, v127
	v_mov_b32_e32 v102, v127
	v_mov_b32_e32 v101, v127
	v_mov_b32_e32 v100, v127
	v_mov_b32_e32 v99, v127
	v_mov_b32_e32 v98, v127
	v_mov_b32_e32 v97, v127
	v_mov_b32_e32 v96, v127
	v_mov_b32_e32 v87, v127
	v_mov_b32_e32 v86, v127
	v_mov_b32_e32 v85, v127
	v_mov_b32_e32 v84, v127
	v_mov_b32_e32 v83, v127
	v_mov_b32_e32 v82, v127
	v_mov_b32_e32 v81, v127
	v_mov_b32_e32 v80, v127
	v_mov_b32_e32 v71, v127
	v_mov_b32_e32 v70, v127
	v_mov_b32_e32 v69, v127
	v_mov_b32_e32 v68, v127
	v_mov_b32_e32 v67, v127
	v_mov_b32_e32 v66, v127
	v_mov_b32_e32 v65, v127
	v_mov_b32_e32 v64, v127
	v_mov_b32_e32 v63, v127
	v_mov_b32_e32 v62, v127
	v_mov_b32_e32 v61, v127
	v_mov_b32_e32 v60, v127
	v_mov_b32_e32 v59, v127
	v_mov_b32_e32 v58, v127
	v_mov_b32_e32 v57, v127
	v_mov_b32_e32 v56, v127
	v_mov_b32_e32 v47, v127
	v_mov_b32_e32 v46, v127
	v_mov_b32_e32 v45, v127
	v_mov_b32_e32 v44, v127
	v_mov_b32_e32 v43, v127
	v_mov_b32_e32 v42, v127
	v_mov_b32_e32 v41, v127
	v_mov_b32_e32 v40, v127
	v_mov_b32_e32 v31, v127
	v_mov_b32_e32 v30, v127
	v_mov_b32_e32 v29, v127
	v_mov_b32_e32 v28, v127
	v_mov_b32_e32 v27, v127
	v_mov_b32_e32 v26, v127
	v_mov_b32_e32 v25, v127
	v_mov_b32_e32 v24, v127
	v_mov_b32_e32 v15, v127
	v_mov_b32_e32 v14, v127
	v_mov_b32_e32 v13, v127
	v_mov_b32_e32 v12, v127
	v_mov_b32_e32 v11, v127
	v_mov_b32_e32 v10, v127
	v_mov_b32_e32 v9, v127
	v_mov_b32_e32 v8, v127
	v_mov_b32_e32 v55, v127
	v_mov_b32_e32 v54, v127
	v_mov_b32_e32 v53, v127
	v_mov_b32_e32 v52, v127
	v_mov_b32_e32 v51, v127
	v_mov_b32_e32 v50, v127
	v_mov_b32_e32 v49, v127
	v_mov_b32_e32 v48, v127
	v_mov_b32_e32 v39, v127
	v_mov_b32_e32 v38, v127
	v_mov_b32_e32 v37, v127
	v_mov_b32_e32 v36, v127
	v_mov_b32_e32 v35, v127
	v_mov_b32_e32 v34, v127
	v_mov_b32_e32 v33, v127
	v_mov_b32_e32 v32, v127
	v_mov_b32_e32 v23, v127
	v_mov_b32_e32 v22, v127
	v_mov_b32_e32 v21, v127
	v_mov_b32_e32 v20, v127
	v_mov_b32_e32 v19, v127
	v_mov_b32_e32 v18, v127
	v_mov_b32_e32 v17, v127
	v_mov_b32_e32 v16, v127
	v_mov_b32_e32 v7, v127
	v_mov_b32_e32 v6, v127
	v_mov_b32_e32 v5, v127
	v_mov_b32_e32 v4, v127
	v_mov_b32_e32 v3, v127
	v_mov_b32_e32 v2, v127
	s_waitcnt lgkmcnt(0)
	v_mov_b32_e32 v1, v127
	v_mov_b32_e32 v0, v127
	s_cbranch_vccnz .LBB0_1754
	s_and_b64 s[12:13], s[12:13], exec
	s_cselect_b32 s23, s27, s39
	s_cselect_b32 s25, s26, s38
	s_cselect_b32 s64, s29, s37
	s_cselect_b32 s65, s28, s36
	s_add_u32 s12, s38, 0x40080
	s_addc_u32 s13, s39, 0
	s_add_u32 s78, s36, 0x100
	s_addc_u32 s79, s37, 0
	s_mov_b32 s36, 0

; #define PG8_STAGE(bufoff, gbase, voff) do { _Pragma("unroll") for (int _i = 0; _i < 2; ++_i) \
;         __builtin_amdgcn_global_load_lds((const unsigned*)((const char*)(gbase) + (voff)[_i]), (LAS unsigned*)(lds + (bufoff) + ldsw + _i * 8192), 16, 0, 0); } while (0)
; #define PG8_WAIT_V(n) asm volatile("s_waitcnt vmcnt(" #n ")" ::: "memory")
; #define PG8_BAR __builtin_amdgcn_s_barrier()
; template <class Epi>
; __device__ __forceinline__ void gemm_phase(LAS unsigned char* lds, const Gemm g, const StaticOrder& S, const Epi& E) {
;     ...
;     f32x4 acc[2][2][4][2];
; #pragma unroll
;     for (int a = 0; a < 2; ++a)
; #pragma unroll
;         for (int b = 0; b < 2; ++b)
; #pragma unroll
;             for (int m = 0; m < 4; ++m)
; #pragma unroll
;                 for (int n = 0; n < 2; ++n) acc[a][b][m][n] = (f32x4){0.f, 0.f, 0.f, 0.f};
;     bf16x8 At[4][2], B0[2][2], B1[2][2];
;     const char* cA = (const char*)g.A + (size_t)cur.pm * tstepA + (size_t)cur.pn * g.a_pn_off * 2; const char* cB = (const char*)g.Bt + (size_t)cur.pn * tstepB;
;     PG8_STAGE(PG8_SB(0, 0), cB, voffB); PG8_STAGE(PG8_SA(0, 0), cA, voffA); PG8_STAGE(PG8_SB(0, 1), cB + hstepB, voffB); PG8_STAGE(PG8_SA(0, 1), cA + hstepA, voffA);
;     if (wr == 1) PG8_BAR;
;     PG8_WAIT_V(4); PG8_BAR;
;     PG8_STAGE(PG8_SB(1, 0), cB + kstep, voffB); PG8_STAGE(PG8_SA(1, 0), cA + kstep, voffA); PG8_STAGE(PG8_SB(1, 1), cB + hstepB + kstep, voffB);
;     PG8_WAIT_V(6); PG8_BAR;
;     for (;;) {
;         const bool has_next = S.next(ui + 1, nxt);
;         const char* nA = has_next ? (const char*)g.A + (size_t)nxt.pm * tstepA + (size_t)nxt.pn * g.a_pn_off * 2 : cA; const char* nB = has_next ? (const char*)g.Bt + (size_t)nxt.pn * tstepB : cB;
;         for (int t = 0; t < nt; t += 2) {
;             const bool last = (t == nt - 2);
;             const char* a1 = cA + (size_t)(t + 1) * kstep;
;             const char* a2 = last ? nA : cA + (size_t)(t + 2) * kstep; const char* b2 = last ? nB : cB + (size_t)(t + 2) * kstep;
.LBB0_1855:
	s_ashr_i32 s23, s22, 31
	s_lshl_b64 s[24:25], s[22:23], 19
	s_add_u32 s24, s70, s24
	s_addc_u32 s25, s71, s25
	s_ashr_i32 s21, s20, 31
	s_lshl_b64 s[26:27], s[20:21], 19
	s_add_u32 s26, s12, s26
	v_mov_b32_e32 v119, 0
	v_cmp_lt_i64_e64 s[8:9], s[8:9], v[140:141]
	s_addc_u32 s27, s13, s27
	s_andn2_b64 vcc, exec, s[18:19]
	v_mov_b32_e32 v118, v119
	v_mov_b32_e32 v117, v119
	v_mov_b32_e32 v116, v119
	v_mov_b32_e32 v127, v119
	v_mov_b32_e32 v126, v119
	v_mov_b32_e32 v125, v119
	v_mov_b32_e32 v124, v119
	v_mov_b32_e32 v111, v119
	v_mov_b32_e32 v110, v119
	v_mov_b32_e32 v109, v119
	v_mov_b32_e32 v108, v119
	v_mov_b32_e32 v107, v119
	v_mov_b32_e32 v106, v119
	v_mov_b32_e32 v105, v119
	v_mov_b32_e32 v104, v119
	v_mov_b32_e32 v95, v119
	v_mov_b32_e32 v94, v119
	v_mov_b32_e32 v93, v119
	v_mov_b32_e32 v92, v119
	v_mov_b32_e32 v91, v119
	v_mov_b32_e32 v90, v119
	v_mov_b32_e32 v89, v119
	v_mov_b32_e32 v88, v119
	v_mov_b32_e32 v79, v119
	v_mov_b32_e32 v78, v119
	v_mov_b32_e32 v77, v119
	v_mov_b32_e32 v76, v119
	v_mov_b32_e32 v75, v119
	v_mov_b32_e32 v74, v119
	v_mov_b32_e32 v73, v119
	v_mov_b32_e32 v72, v119
	v_mov_b32_e32 v123, v119
	v_mov_b32_e32 v122, v119
	v_mov_b32_e32 v121, v119
	v_mov_b32_e32 v120, v119
	v_mov_b32_e32 v115, v119
	v_mov_b32_e32 v114, v119
	v_mov_b32_e32 v113, v119
	v_mov_b32_e32 v112, v119
	v_mov_b32_e32 v103, v119
	v_mov_b32_e32 v102, v119
	v_mov_b32_e32 v101, v119
	v_mov_b32_e32 v100, v119
	v_mov_b32_e32 v99, v119
	v_mov_b32_e32 v98, v119
	v_mov_b32_e32 v97, v119
	v_mov_b32_e32 v96, v119
	v_mov_b32_e32 v87, v119
	v_mov_b32_e32 v86, v119
	v_mov_b32_e32 v85, v119
	v_mov_b32_e32 v84, v119
	v_mov_b32_e32 v83, v119
	v_mov_b32_e32 v82, v119
	v_mov_b32_e32 v81, v119
	v_mov_b32_e32 v80, v119
	v_mov_b32_e32 v71, v119
	v_mov_b32_e32 v70, v119
	v_mov_b32_e32 v69, v119
	v_mov_b32_e32 v68, v119
	v_mov_b32_e32 v67, v119
	v_mov_b32_e32 v66, v119
	v_mov_b32_e32 v65, v119
	v_mov_b32_e32 v64, v119
	v_mov_b32_e32 v63, v119
	v_mov_b32_e32 v62, v119
	v_mov_b32_e32 v61, v119
	v_mov_b32_e32 v60, v119
	v_mov_b32_e32 v59, v119
	v_mov_b32_e32 v58, v119
	v_mov_b32_e32 v57, v119
	v_mov_b32_e32 v56, v119
	v_mov_b32_e32 v47, v119
	v_mov_b32_e32 v46, v119
	v_mov_b32_e32 v45, v119
	v_mov_b32_e32 v44, v119
	v_mov_b32_e32 v43, v119
	v_mov_b32_e32 v42, v119
	v_mov_b32_e32 v41, v119
	v_mov_b32_e32 v40, v119
	v_mov_b32_e32 v31, v119
	v_mov_b32_e32 v30, v119
	v_mov_b32_e32 v29, v119
	v_mov_b32_e32 v28, v119
	v_mov_b32_e32 v27, v119
	v_mov_b32_e32 v26, v119
	v_mov_b32_e32 v25, v119
	v_mov_b32_e32 v24, v119
	v_mov_b32_e32 v15, v119
	v_mov_b32_e32 v14, v119
	v_mov_b32_e32 v13, v119
	v_mov_b32_e32 v12, v119
	v_mov_b32_e32 v11, v119
	v_mov_b32_e32 v10, v119
	v_mov_b32_e32 v9, v119
	v_mov_b32_e32 v8, v119
	v_mov_b32_e32 v55, v119
	v_mov_b32_e32 v54, v119
	v_mov_b32_e32 v53, v119
	v_mov_b32_e32 v52, v119
	v_mov_b32_e32 v51, v119
	v_mov_b32_e32 v50, v119
	v_mov_b32_e32 v49, v119
	v_mov_b32_e32 v48, v119
	v_mov_b32_e32 v39, v119
	v_mov_b32_e32 v38, v119
	v_mov_b32_e32 v37, v119
	v_mov_b32_e32 v36, v119
	v_mov_b32_e32 v35, v119
	v_mov_b32_e32 v34, v119
	v_mov_b32_e32 v33, v119
	v_mov_b32_e32 v32, v119
	v_mov_b32_e32 v23, v119
	v_mov_b32_e32 v22, v119
	v_mov_b32_e32 v21, v119
	v_mov_b32_e32 v20, v119
	v_mov_b32_e32 v19, v119
	v_mov_b32_e32 v18, v119
	v_mov_b32_e32 v17, v119
	v_mov_b32_e32 v16, v119
	v_mov_b32_e32 v7, v119
	v_mov_b32_e32 v6, v119
	v_mov_b32_e32 v5, v119
	v_mov_b32_e32 v4, v119
	v_mov_b32_e32 v3, v119
	v_mov_b32_e32 v2, v119
	v_mov_b32_e32 v1, v119
	v_mov_b32_e32 v0, v119
	s_cbranch_vccnz .LBB0_1858
	s_and_b64 s[8:9], s[8:9], exec
	s_cselect_b32 s21, s25, s37
	s_cselect_b32 s23, s24, s36
	s_cselect_b32 s65, s27, s31
	s_cselect_b32 s77, s26, s30
	s_add_u32 s8, s36, 0x40080
	s_addc_u32 s9, s37, 0
	s_add_u32 s78, s30, 0x100
	s_addc_u32 s79, s31, 0
	s_mov_b32 s30, 0

; #define PG8_STAGE(bufoff, gbase, voff) do { _Pragma("unroll") for (int _i = 0; _i < 2; ++_i) \
;         __builtin_amdgcn_global_load_lds((const unsigned*)((const char*)(gbase) + (voff)[_i]), (LAS unsigned*)(lds + (bufoff) + ldsw + _i * 8192), 16, 0, 0); } while (0)
; #define PG8_WAIT_V(n) asm volatile("s_waitcnt vmcnt(" #n ")" ::: "memory")
; #define PG8_BAR __builtin_amdgcn_s_barrier()
; template <class Epi>
; __device__ __forceinline__ void gemm_phase(LAS unsigned char* lds, const Gemm g, const StaticOrder& S, const Epi& E) {
;     ...
;     f32x4 acc[2][2][4][2];
; #pragma unroll
;     for (int a = 0; a < 2; ++a)
; #pragma unroll
;         for (int b = 0; b < 2; ++b)
; #pragma unroll
;             for (int m = 0; m < 4; ++m)
; #pragma unroll
;                 for (int n = 0; n < 2; ++n) acc[a][b][m][n] = (f32x4){0.f, 0.f, 0.f, 0.f};
;     bf16x8 At[4][2], B0[2][2], B1[2][2];
;     const char* cA = (const char*)g.A + (size_t)cur.pm * tstepA + (size_t)cur.pn * g.a_pn_off * 2; const char* cB = (const char*)g.Bt + (size_t)cur.pn * tstepB;
;     PG8_STAGE(PG8_SB(0, 0), cB, voffB); PG8_STAGE(PG8_SA(0, 0), cA, voffA); PG8_STAGE(PG8_SB(0, 1), cB + hstepB, voffB); PG8_STAGE(PG8_SA(0, 1), cA + hstepA, voffA);
;     if (wr == 1) PG8_BAR;
;     PG8_WAIT_V(4); PG8_BAR;
;     PG8_STAGE(PG8_SB(1, 0), cB + kstep, voffB); PG8_STAGE(PG8_SA(1, 0), cA + kstep, voffA); PG8_STAGE(PG8_SB(1, 1), cB + hstepB + kstep, voffB);
;     PG8_WAIT_V(6); PG8_BAR;
;     for (;;) {
;         const bool has_next = S.next(ui + 1, nxt);
;         const char* nA = has_next ? (const char*)g.A + (size_t)nxt.pm * tstepA + (size_t)nxt.pn * g.a_pn_off * 2 : cA; const char* nB = has_next ? (const char*)g.Bt + (size_t)nxt.pn * tstepB : cB;
;         for (int t = 0; t < nt; t += 2) {
;             const bool last = (t == nt - 2);
;             const char* a1 = cA + (size_t)(t + 1) * kstep;
;             const char* a2 = last ? nA : cA + (size_t)(t + 2) * kstep; const char* b2 = last ? nB : cB + (size_t)(t + 2) * kstep;
.LBB0_1893:
	s_ashr_i32 s63, s62, 31
	s_lshl_b64 s[14:15], s[62:63], 19
	s_add_u32 s76, s36, s14
	s_addc_u32 s77, s37, s15
	s_ashr_i32 s61, s60, 31
	s_lshl_b64 s[14:15], s[60:61], 19
	s_add_u32 s78, s70, s14
	v_mov_b32_e32 v127, 0
	v_cmp_lt_i64_e64 s[8:9], s[8:9], v[140:141]
	s_addc_u32 s79, s71, s15
	s_andn2_b64 vcc, exec, s[42:43]
	v_mov_b32_e32 v126, v127
	v_mov_b32_e32 v125, v127
	v_mov_b32_e32 v124, v127
	v_mov_b32_e32 v123, v127
	v_mov_b32_e32 v122, v127
	v_mov_b32_e32 v121, v127
	v_mov_b32_e32 v120, v127
	v_mov_b32_e32 v111, v127
	v_mov_b32_e32 v110, v127
	v_mov_b32_e32 v109, v127
	v_mov_b32_e32 v108, v127
	v_mov_b32_e32 v107, v127
	v_mov_b32_e32 v106, v127
	v_mov_b32_e32 v105, v127
	v_mov_b32_e32 v104, v127
	v_mov_b32_e32 v95, v127
	v_mov_b32_e32 v94, v127
	v_mov_b32_e32 v93, v127
	v_mov_b32_e32 v92, v127
	v_mov_b32_e32 v91, v127
	v_mov_b32_e32 v90, v127
	v_mov_b32_e32 v89, v127
	v_mov_b32_e32 v88, v127
	v_mov_b32_e32 v79, v127
	v_mov_b32_e32 v78, v127
	v_mov_b32_e32 v77, v127
	v_mov_b32_e32 v76, v127
	v_mov_b32_e32 v75, v127
	v_mov_b32_e32 v74, v127
	v_mov_b32_e32 v73, v127
	v_mov_b32_e32 v72, v127
	v_mov_b32_e32 v119, v127
	v_mov_b32_e32 v118, v127
	v_mov_b32_e32 v117, v127
	v_mov_b32_e32 v116, v127
	v_mov_b32_e32 v115, v127
	v_mov_b32_e32 v114, v127
	v_mov_b32_e32 v113, v127
	v_mov_b32_e32 v112, v127
	v_mov_b32_e32 v103, v127
	v_mov_b32_e32 v102, v127
	v_mov_b32_e32 v101, v127
	v_mov_b32_e32 v100, v127
	v_mov_b32_e32 v99, v127
	v_mov_b32_e32 v98, v127
	v_mov_b32_e32 v97, v127
	v_mov_b32_e32 v96, v127
	v_mov_b32_e32 v87, v127
	v_mov_b32_e32 v86, v127
	v_mov_b32_e32 v85, v127
	v_mov_b32_e32 v84, v127
	v_mov_b32_e32 v83, v127
	v_mov_b32_e32 v82, v127
	v_mov_b32_e32 v81, v127
	v_mov_b32_e32 v80, v127
	v_mov_b32_e32 v71, v127
	v_mov_b32_e32 v70, v127
	v_mov_b32_e32 v69, v127
	v_mov_b32_e32 v68, v127
	v_mov_b32_e32 v67, v127
	v_mov_b32_e32 v66, v127
	v_mov_b32_e32 v65, v127
	v_mov_b32_e32 v64, v127
	v_mov_b32_e32 v63, v127
	v_mov_b32_e32 v62, v127
	v_mov_b32_e32 v61, v127
	v_mov_b32_e32 v60, v127
	v_mov_b32_e32 v59, v127
	v_mov_b32_e32 v58, v127
	v_mov_b32_e32 v57, v127
	v_mov_b32_e32 v56, v127
	v_mov_b32_e32 v47, v127
	v_mov_b32_e32 v46, v127
	v_mov_b32_e32 v45, v127
	v_mov_b32_e32 v44, v127
	v_mov_b32_e32 v43, v127
	v_mov_b32_e32 v42, v127
	v_mov_b32_e32 v41, v127
	v_mov_b32_e32 v40, v127
	v_mov_b32_e32 v31, v127
	v_mov_b32_e32 v30, v127
	v_mov_b32_e32 v29, v127
	v_mov_b32_e32 v28, v127
	v_mov_b32_e32 v27, v127
	v_mov_b32_e32 v26, v127
	v_mov_b32_e32 v25, v127
	v_mov_b32_e32 v24, v127
	v_mov_b32_e32 v15, v127
	v_mov_b32_e32 v14, v127
	v_mov_b32_e32 v13, v127
	v_mov_b32_e32 v12, v127
	v_mov_b32_e32 v11, v127
	v_mov_b32_e32 v10, v127
	v_mov_b32_e32 v9, v127
	v_mov_b32_e32 v8, v127
	v_mov_b32_e32 v55, v127
	v_mov_b32_e32 v54, v127
	v_mov_b32_e32 v53, v127
	v_mov_b32_e32 v52, v127
	v_mov_b32_e32 v51, v127
	v_mov_b32_e32 v50, v127
	v_mov_b32_e32 v49, v127
	v_mov_b32_e32 v48, v127
	v_mov_b32_e32 v39, v127
	v_mov_b32_e32 v38, v127
	v_mov_b32_e32 v37, v127
	v_mov_b32_e32 v36, v127
	v_mov_b32_e32 v35, v127
	v_mov_b32_e32 v34, v127
	v_mov_b32_e32 v33, v127
	v_mov_b32_e32 v32, v127
	v_mov_b32_e32 v23, v127
	v_mov_b32_e32 v22, v127
	v_mov_b32_e32 v21, v127
	v_mov_b32_e32 v20, v127
	v_mov_b32_e32 v19, v127
	v_mov_b32_e32 v18, v127
	v_mov_b32_e32 v17, v127
	v_mov_b32_e32 v16, v127
	v_mov_b32_e32 v7, v127
	v_mov_b32_e32 v6, v127
	v_mov_b32_e32 v5, v127
	v_mov_b32_e32 v4, v127
	v_mov_b32_e32 v3, v127
	v_mov_b32_e32 v2, v127
	v_mov_b32_e32 v1, v127
	v_mov_b32_e32 v0, v127
	s_cbranch_vccnz .LBB0_1886
	s_and_b64 s[8:9], s[8:9], exec
	s_cselect_b32 s14, s77, s13
	s_cselect_b32 s15, s76, s12
	s_cselect_b32 s17, s79, s11
	s_cselect_b32 s18, s78, s10
	s_add_u32 s8, s12, 0x40080
	s_addc_u32 s9, s13, 0
	s_add_u32 s19, s10, 0x100
	s_addc_u32 s20, s11, 0
	s_mov_b32 s10, 0

; #define PG8_STAGE(bufoff, gbase, voff) do { _Pragma("unroll") for (int _i = 0; _i < 2; ++_i) \
;         __builtin_amdgcn_global_load_lds((const unsigned*)((const char*)(gbase) + (voff)[_i]), (LAS unsigned*)(lds + (bufoff) + ldsw + _i * 8192), 16, 0, 0); } while (0)
; #define PG8_WAIT_V(n) asm volatile("s_waitcnt vmcnt(" #n ")" ::: "memory")
; #define PG8_BAR __builtin_amdgcn_s_barrier()
; template <class Epi>
; __device__ __forceinline__ void gemm_phase(LAS unsigned char* lds, const Gemm g, const StaticOrder& S, const Epi& E) {
;     ...
;     f32x4 acc[2][2][4][2];
; #pragma unroll
;     for (int a = 0; a < 2; ++a)
; #pragma unroll
;         for (int b = 0; b < 2; ++b)
; #pragma unroll
;             for (int m = 0; m < 4; ++m)
; #pragma unroll
;                 for (int n = 0; n < 2; ++n) acc[a][b][m][n] = (f32x4){0.f, 0.f, 0.f, 0.f};
;     bf16x8 At[4][2], B0[2][2], B1[2][2];
;     const char* cA = (const char*)g.A + (size_t)cur.pm * tstepA + (size_t)cur.pn * g.a_pn_off * 2; const char* cB = (const char*)g.Bt + (size_t)cur.pn * tstepB;
;     PG8_STAGE(PG8_SB(0, 0), cB, voffB); PG8_STAGE(PG8_SA(0, 0), cA, voffA); PG8_STAGE(PG8_SB(0, 1), cB + hstepB, voffB); PG8_STAGE(PG8_SA(0, 1), cA + hstepA, voffA);
;     if (wr == 1) PG8_BAR;
;     PG8_WAIT_V(4); PG8_BAR;
;     PG8_STAGE(PG8_SB(1, 0), cB + kstep, voffB); PG8_STAGE(PG8_SA(1, 0), cA + kstep, voffA); PG8_STAGE(PG8_SB(1, 1), cB + hstepB + kstep, voffB);
;     PG8_WAIT_V(6); PG8_BAR;
;     for (;;) {
;         const bool has_next = S.next(ui + 1, nxt);
;         const char* nA = has_next ? (const char*)g.A + (size_t)nxt.pm * tstepA + (size_t)nxt.pn * g.a_pn_off * 2 : cA; const char* nB = has_next ? (const char*)g.Bt + (size_t)nxt.pn * tstepB : cB;
;         for (int t = 0; t < nt; t += 2) {
;             const bool last = (t == nt - 2);
;             const char* a1 = cA + (size_t)(t + 1) * kstep;
;             const char* a2 = last ? nA : cA + (size_t)(t + 2) * kstep; const char* b2 = last ? nB : cB + (size_t)(t + 2) * kstep;
.LBB0_2294:
	s_ashr_i32 s23, s22, 31
	s_lshl_b64 s[24:25], s[22:23], 19
	s_add_u32 s24, s70, s24
	s_addc_u32 s25, s71, s25
	s_ashr_i32 s21, s20, 31
	s_lshl_b64 s[26:27], s[20:21], 19
	s_add_u32 s26, s16, s26
	v_mov_b32_e32 v127, 0
	v_cmp_lt_i64_e64 s[12:13], s[12:13], v[188:189]
	s_addc_u32 s27, s17, s27
	s_and_b64 vcc, exec, s[8:9]
	v_mov_b32_e32 v126, v127
	v_mov_b32_e32 v125, v127
	v_mov_b32_e32 v124, v127
	v_mov_b32_e32 v123, v127
	v_mov_b32_e32 v122, v127
	v_mov_b32_e32 v121, v127
	v_mov_b32_e32 v120, v127
	v_mov_b32_e32 v111, v127
	v_mov_b32_e32 v110, v127
	v_mov_b32_e32 v109, v127
	v_mov_b32_e32 v108, v127
	v_mov_b32_e32 v107, v127
	v_mov_b32_e32 v106, v127
	v_mov_b32_e32 v105, v127
	v_mov_b32_e32 v104, v127
	v_mov_b32_e32 v95, v127
	v_mov_b32_e32 v94, v127
	v_mov_b32_e32 v93, v127
	v_mov_b32_e32 v92, v127
	v_mov_b32_e32 v91, v127
	v_mov_b32_e32 v90, v127
	v_mov_b32_e32 v89, v127
	v_mov_b32_e32 v88, v127
	v_mov_b32_e32 v79, v127
	v_mov_b32_e32 v78, v127
	v_mov_b32_e32 v77, v127
	v_mov_b32_e32 v76, v127
	v_mov_b32_e32 v75, v127
	v_mov_b32_e32 v74, v127
	v_mov_b32_e32 v73, v127
	v_mov_b32_e32 v72, v127
	v_mov_b32_e32 v119, v127
	v_mov_b32_e32 v118, v127
	v_mov_b32_e32 v117, v127
	v_mov_b32_e32 v116, v127
	v_mov_b32_e32 v115, v127
	v_mov_b32_e32 v114, v127
	v_mov_b32_e32 v113, v127
	v_mov_b32_e32 v112, v127
	v_mov_b32_e32 v103, v127
	v_mov_b32_e32 v102, v127
	v_mov_b32_e32 v101, v127
	v_mov_b32_e32 v100, v127
	v_mov_b32_e32 v99, v127
	v_mov_b32_e32 v98, v127
	v_mov_b32_e32 v97, v127
	v_mov_b32_e32 v96, v127
	v_mov_b32_e32 v87, v127
	v_mov_b32_e32 v86, v127
	v_mov_b32_e32 v85, v127
	v_mov_b32_e32 v84, v127
	v_mov_b32_e32 v83, v127
	v_mov_b32_e32 v82, v127
	v_mov_b32_e32 v81, v127
	v_mov_b32_e32 v80, v127
	v_mov_b32_e32 v71, v127
	v_mov_b32_e32 v70, v127
	v_mov_b32_e32 v69, v127
	v_mov_b32_e32 v68, v127
	v_mov_b32_e32 v67, v127
	v_mov_b32_e32 v66, v127
	v_mov_b32_e32 v65, v127
	v_mov_b32_e32 v64, v127
	v_mov_b32_e32 v63, v127
	v_mov_b32_e32 v62, v127
	v_mov_b32_e32 v61, v127
	v_mov_b32_e32 v60, v127
	v_mov_b32_e32 v59, v127
	v_mov_b32_e32 v58, v127
	v_mov_b32_e32 v57, v127
	v_mov_b32_e32 v56, v127
	v_mov_b32_e32 v47, v127
	v_mov_b32_e32 v46, v127
	v_mov_b32_e32 v45, v127
	v_mov_b32_e32 v44, v127
	v_mov_b32_e32 v43, v127
	v_mov_b32_e32 v42, v127
	v_mov_b32_e32 v41, v127
	v_mov_b32_e32 v40, v127
	v_mov_b32_e32 v31, v127
	v_mov_b32_e32 v30, v127
	v_mov_b32_e32 v29, v127
	v_mov_b32_e32 v28, v127
	v_mov_b32_e32 v27, v127
	v_mov_b32_e32 v26, v127
	v_mov_b32_e32 v25, v127
	v_mov_b32_e32 v24, v127
	v_mov_b32_e32 v15, v127
	v_mov_b32_e32 v14, v127
	v_mov_b32_e32 v13, v127
	v_mov_b32_e32 v12, v127
	v_mov_b32_e32 v11, v127
	v_mov_b32_e32 v10, v127
	v_mov_b32_e32 v9, v127
	v_mov_b32_e32 v8, v127
	v_mov_b32_e32 v55, v127
	v_mov_b32_e32 v54, v127
	v_mov_b32_e32 v53, v127
	v_mov_b32_e32 v52, v127
	v_mov_b32_e32 v51, v127
	v_mov_b32_e32 v50, v127
	v_mov_b32_e32 v49, v127
	v_mov_b32_e32 v48, v127
	v_mov_b32_e32 v39, v127
	v_mov_b32_e32 v38, v127
	v_mov_b32_e32 v37, v127
	v_mov_b32_e32 v36, v127
	v_mov_b32_e32 v35, v127
	v_mov_b32_e32 v34, v127
	v_mov_b32_e32 v33, v127
	v_mov_b32_e32 v32, v127
	v_mov_b32_e32 v23, v127
	v_mov_b32_e32 v22, v127
	v_mov_b32_e32 v21, v127
	v_mov_b32_e32 v20, v127
	v_mov_b32_e32 v19, v127
	v_mov_b32_e32 v18, v127
	v_mov_b32_e32 v17, v127
	v_mov_b32_e32 v16, v127
	v_mov_b32_e32 v7, v127
	v_mov_b32_e32 v6, v127
	v_mov_b32_e32 v5, v127
	v_mov_b32_e32 v4, v127
	v_mov_b32_e32 v3, v127
	v_mov_b32_e32 v2, v127
	s_waitcnt lgkmcnt(0)
	v_mov_b32_e32 v1, v127
	v_mov_b32_e32 v0, v127
	s_cbranch_vccnz .LBB0_2297
	s_and_b64 s[12:13], s[12:13], exec
	s_cselect_b32 s21, s25, s37
	s_cselect_b32 s23, s24, s36
	s_cselect_b32 s63, s27, s35
	s_cselect_b32 s64, s26, s34
	s_add_u32 s12, s36, 0x40080
	s_addc_u32 s13, s37, 0
	s_add_u32 s65, s34, 0x100
	s_addc_u32 s76, s35, 0
	s_mov_b32 s34, 0

; #define PG8_STAGE(bufoff, gbase, voff) do { _Pragma("unroll") for (int _i = 0; _i < 2; ++_i) \
;         __builtin_amdgcn_global_load_lds((const unsigned*)((const char*)(gbase) + (voff)[_i]), (LAS unsigned*)(lds + (bufoff) + ldsw + _i * 8192), 16, 0, 0); } while (0)
; #define PG8_WAIT_V(n) asm volatile("s_waitcnt vmcnt(" #n ")" ::: "memory")
; #define PG8_BAR __builtin_amdgcn_s_barrier()
; template <class Epi>
; __device__ __forceinline__ void gemm_phase(LAS unsigned char* lds, const Gemm g, const StaticOrder& S, const Epi& E) {
;     ...
;     f32x4 acc[2][2][4][2];
; #pragma unroll
;     for (int a = 0; a < 2; ++a)
; #pragma unroll
;         for (int b = 0; b < 2; ++b)
; #pragma unroll
;             for (int m = 0; m < 4; ++m)
; #pragma unroll
;                 for (int n = 0; n < 2; ++n) acc[a][b][m][n] = (f32x4){0.f, 0.f, 0.f, 0.f};
;     bf16x8 At[4][2], B0[2][2], B1[2][2];
;     const char* cA = (const char*)g.A + (size_t)cur.pm * tstepA + (size_t)cur.pn * g.a_pn_off * 2; const char* cB = (const char*)g.Bt + (size_t)cur.pn * tstepB;
;     PG8_STAGE(PG8_SB(0, 0), cB, voffB); PG8_STAGE(PG8_SA(0, 0), cA, voffA); PG8_STAGE(PG8_SB(0, 1), cB + hstepB, voffB); PG8_STAGE(PG8_SA(0, 1), cA + hstepA, voffA);
;     if (wr == 1) PG8_BAR;
;     PG8_WAIT_V(4); PG8_BAR;
;     PG8_STAGE(PG8_SB(1, 0), cB + kstep, voffB); PG8_STAGE(PG8_SA(1, 0), cA + kstep, voffA); PG8_STAGE(PG8_SB(1, 1), cB + hstepB + kstep, voffB);
;     PG8_WAIT_V(6); PG8_BAR;
;     for (;;) {
;         const bool has_next = S.next(ui + 1, nxt);
;         const char* nA = has_next ? (const char*)g.A + (size_t)nxt.pm * tstepA + (size_t)nxt.pn * g.a_pn_off * 2 : cA; const char* nB = has_next ? (const char*)g.Bt + (size_t)nxt.pn * tstepB : cB;
;         for (int t = 0; t < nt; t += 2) {
;             const bool last = (t == nt - 2);
;             const char* a1 = cA + (size_t)(t + 1) * kstep;
;             const char* a2 = last ? nA : cA + (size_t)(t + 2) * kstep; const char* b2 = last ? nB : cB + (size_t)(t + 2) * kstep;
.LBB0_2409:
	s_ashr_i32 s19, s18, 31
	s_lshl_b64 s[20:21], s[18:19], 19
	s_add_u32 s20, s68, s20
	s_addc_u32 s21, s69, s21
	s_ashr_i32 s17, s16, 31
	s_lshl_b64 s[22:23], s[16:17], 19
	s_add_u32 s22, s31, s22
	v_mov_b32_e32 v119, 0
	v_cmp_lt_i64_e64 s[8:9], s[8:9], v[140:141]
	s_addc_u32 s23, s34, s23
	s_andn2_b64 vcc, exec, s[14:15]
	v_mov_b32_e32 v118, v119
	v_mov_b32_e32 v117, v119
	v_mov_b32_e32 v116, v119
	v_mov_b32_e32 v115, v119
	v_mov_b32_e32 v114, v119
	v_mov_b32_e32 v113, v119
	v_mov_b32_e32 v112, v119
	v_mov_b32_e32 v107, v119
	v_mov_b32_e32 v106, v119
	v_mov_b32_e32 v105, v119
	v_mov_b32_e32 v104, v119
	v_mov_b32_e32 v99, v119
	v_mov_b32_e32 v98, v119
	v_mov_b32_e32 v97, v119
	v_mov_b32_e32 v96, v119
	v_mov_b32_e32 v91, v119
	v_mov_b32_e32 v90, v119
	v_mov_b32_e32 v89, v119
	v_mov_b32_e32 v88, v119
	v_mov_b32_e32 v83, v119
	v_mov_b32_e32 v82, v119
	v_mov_b32_e32 v81, v119
	v_mov_b32_e32 v80, v119
	v_mov_b32_e32 v75, v119
	v_mov_b32_e32 v74, v119
	v_mov_b32_e32 v73, v119
	v_mov_b32_e32 v72, v119
	v_mov_b32_e32 v67, v119
	v_mov_b32_e32 v66, v119
	v_mov_b32_e32 v65, v119
	v_mov_b32_e32 v64, v119
	v_mov_b32_e32 v127, v119
	v_mov_b32_e32 v126, v119
	v_mov_b32_e32 v125, v119
	v_mov_b32_e32 v124, v119
	v_mov_b32_e32 v123, v119
	v_mov_b32_e32 v122, v119
	v_mov_b32_e32 v121, v119
	v_mov_b32_e32 v120, v119
	v_mov_b32_e32 v111, v119
	v_mov_b32_e32 v110, v119
	v_mov_b32_e32 v109, v119
	v_mov_b32_e32 v108, v119
	v_mov_b32_e32 v103, v119
	v_mov_b32_e32 v102, v119
	v_mov_b32_e32 v101, v119
	v_mov_b32_e32 v100, v119
	v_mov_b32_e32 v95, v119
	v_mov_b32_e32 v94, v119
	v_mov_b32_e32 v93, v119
	v_mov_b32_e32 v92, v119
	v_mov_b32_e32 v87, v119
	v_mov_b32_e32 v86, v119
	v_mov_b32_e32 v85, v119
	v_mov_b32_e32 v84, v119
	v_mov_b32_e32 v79, v119
	v_mov_b32_e32 v78, v119
	v_mov_b32_e32 v77, v119
	v_mov_b32_e32 v76, v119
	v_mov_b32_e32 v71, v119
	v_mov_b32_e32 v70, v119
	v_mov_b32_e32 v69, v119
	v_mov_b32_e32 v68, v119
	v_mov_b32_e32 v59, v119
	v_mov_b32_e32 v58, v119
	v_mov_b32_e32 v57, v119
	v_mov_b32_e32 v56, v119
	v_mov_b32_e32 v51, v119
	v_mov_b32_e32 v50, v119
	v_mov_b32_e32 v49, v119
	v_mov_b32_e32 v48, v119
	v_mov_b32_e32 v43, v119
	v_mov_b32_e32 v42, v119
	v_mov_b32_e32 v41, v119
	v_mov_b32_e32 v40, v119
	v_mov_b32_e32 v35, v119
	v_mov_b32_e32 v34, v119
	v_mov_b32_e32 v33, v119
	v_mov_b32_e32 v32, v119
	v_mov_b32_e32 v27, v119
	v_mov_b32_e32 v26, v119
	v_mov_b32_e32 v25, v119
	v_mov_b32_e32 v24, v119
	v_mov_b32_e32 v19, v119
	v_mov_b32_e32 v18, v119
	v_mov_b32_e32 v17, v119
	v_mov_b32_e32 v16, v119
	v_mov_b32_e32 v11, v119
	v_mov_b32_e32 v10, v119
	v_mov_b32_e32 v9, v119
	v_mov_b32_e32 v8, v119
	v_mov_b32_e32 v7, v119
	v_mov_b32_e32 v6, v119
	v_mov_b32_e32 v5, v119
	v_mov_b32_e32 v4, v119
	v_mov_b32_e32 v63, v119
	v_mov_b32_e32 v62, v119
	v_mov_b32_e32 v61, v119
	v_mov_b32_e32 v60, v119
	v_mov_b32_e32 v55, v119
	v_mov_b32_e32 v54, v119
	v_mov_b32_e32 v53, v119
	v_mov_b32_e32 v52, v119
	v_mov_b32_e32 v47, v119
	v_mov_b32_e32 v46, v119
	v_mov_b32_e32 v45, v119
	v_mov_b32_e32 v44, v119
	v_mov_b32_e32 v39, v119
	v_mov_b32_e32 v38, v119
	v_mov_b32_e32 v37, v119
	v_mov_b32_e32 v36, v119
	v_mov_b32_e32 v31, v119
	v_mov_b32_e32 v30, v119
	v_mov_b32_e32 v29, v119
	v_mov_b32_e32 v28, v119
	v_mov_b32_e32 v23, v119
	v_mov_b32_e32 v22, v119
	v_mov_b32_e32 v21, v119
	v_mov_b32_e32 v20, v119
	v_mov_b32_e32 v15, v119
	v_mov_b32_e32 v14, v119
	v_mov_b32_e32 v13, v119
	v_mov_b32_e32 v12, v119
	v_mov_b32_e32 v3, v119
	v_mov_b32_e32 v2, v119
	v_mov_b32_e32 v1, v119
	v_mov_b32_e32 v0, v119
	s_cbranch_vccnz .LBB0_2402
	s_and_b64 s[8:9], s[8:9], exec
	s_cselect_b32 s17, s21, s29
	s_cselect_b32 s19, s20, s28
	s_cselect_b32 s63, s23, s27
	s_cselect_b32 s64, s22, s26
	s_add_u32 s8, s28, 0x40080
	s_addc_u32 s9, s29, 0
	s_add_u32 s65, s26, 0x100
	s_addc_u32 s76, s27, 0
	s_mov_b32 s26, 0

; #define PG8_STAGE(bufoff, gbase, voff) do { _Pragma("unroll") for (int _i = 0; _i < 2; ++_i) \
;         __builtin_amdgcn_global_load_lds((const unsigned*)((const char*)(gbase) + (voff)[_i]), (LAS unsigned*)(lds + (bufoff) + ldsw + _i * 8192), 16, 0, 0); } while (0)
; #define PG8_WAIT_V(n) asm volatile("s_waitcnt vmcnt(" #n ")" ::: "memory")
; #define PG8_BAR __builtin_amdgcn_s_barrier()
; template <class Epi>
; __device__ __forceinline__ void gemm_phase(LAS unsigned char* lds, const Gemm g, const StaticOrder& S, const Epi& E) {
;     ...
;     f32x4 acc[2][2][4][2];
; #pragma unroll
;     for (int a = 0; a < 2; ++a)
; #pragma unroll
;         for (int b = 0; b < 2; ++b)
; #pragma unroll
;             for (int m = 0; m < 4; ++m)
; #pragma unroll
;                 for (int n = 0; n < 2; ++n) acc[a][b][m][n] = (f32x4){0.f, 0.f, 0.f, 0.f};
;     bf16x8 At[4][2], B0[2][2], B1[2][2];
;     const char* cA = (const char*)g.A + (size_t)cur.pm * tstepA + (size_t)cur.pn * g.a_pn_off * 2; const char* cB = (const char*)g.Bt + (size_t)cur.pn * tstepB;
;     PG8_STAGE(PG8_SB(0, 0), cB, voffB); PG8_STAGE(PG8_SA(0, 0), cA, voffA); PG8_STAGE(PG8_SB(0, 1), cB + hstepB, voffB); PG8_STAGE(PG8_SA(0, 1), cA + hstepA, voffA);
;     if (wr == 1) PG8_BAR;
;     PG8_WAIT_V(4); PG8_BAR;
;     PG8_STAGE(PG8_SB(1, 0), cB + kstep, voffB); PG8_STAGE(PG8_SA(1, 0), cA + kstep, voffA); PG8_STAGE(PG8_SB(1, 1), cB + hstepB + kstep, voffB);
;     PG8_WAIT_V(6); PG8_BAR;
;     for (;;) {
;         const bool has_next = S.next(ui + 1, nxt);
;         const char* nA = has_next ? (const char*)g.A + (size_t)nxt.pm * tstepA + (size_t)nxt.pn * g.a_pn_off * 2 : cA; const char* nB = has_next ? (const char*)g.Bt + (size_t)nxt.pn * tstepB : cB;
;         for (int t = 0; t < nt; t += 2) {
;             const bool last = (t == nt - 2);
;             const char* a1 = cA + (size_t)(t + 1) * kstep;
;             const char* a2 = last ? nA : cA + (size_t)(t + 2) * kstep; const char* b2 = last ? nB : cB + (size_t)(t + 2) * kstep;
.LBB0_2431:
	s_ashr_i32 s23, s22, 31
	s_lshl_b64 s[24:25], s[22:23], 17
	s_add_u32 s24, s14, s24
	s_addc_u32 s25, s15, s25
	s_ashr_i32 s21, s20, 31
	s_lshl_b64 s[26:27], s[20:21], 17
	s_add_u32 s26, s12, s26
	v_mov_b32_e32 v127, 0
	v_cmp_lt_i64_e64 s[10:11], s[10:11], v[140:141]
	s_addc_u32 s27, s13, s27
	s_and_b64 vcc, exec, s[6:7]
	v_mov_b32_e32 v126, v127
	v_mov_b32_e32 v125, v127
	v_mov_b32_e32 v124, v127
	v_mov_b32_e32 v123, v127
	v_mov_b32_e32 v122, v127
	v_mov_b32_e32 v121, v127
	v_mov_b32_e32 v120, v127
	v_mov_b32_e32 v111, v127
	v_mov_b32_e32 v110, v127
	v_mov_b32_e32 v109, v127
	v_mov_b32_e32 v108, v127
	v_mov_b32_e32 v107, v127
	v_mov_b32_e32 v106, v127
	v_mov_b32_e32 v105, v127
	v_mov_b32_e32 v104, v127
	v_mov_b32_e32 v95, v127
	v_mov_b32_e32 v94, v127
	v_mov_b32_e32 v93, v127
	v_mov_b32_e32 v92, v127
	v_mov_b32_e32 v91, v127
	v_mov_b32_e32 v90, v127
	v_mov_b32_e32 v89, v127
	v_mov_b32_e32 v88, v127
	v_mov_b32_e32 v79, v127
	v_mov_b32_e32 v78, v127
	v_mov_b32_e32 v77, v127
	v_mov_b32_e32 v76, v127
	v_mov_b32_e32 v75, v127
	v_mov_b32_e32 v74, v127
	v_mov_b32_e32 v73, v127
	v_mov_b32_e32 v72, v127
	v_mov_b32_e32 v119, v127
	v_mov_b32_e32 v118, v127
	v_mov_b32_e32 v117, v127
	v_mov_b32_e32 v116, v127
	v_mov_b32_e32 v115, v127
	v_mov_b32_e32 v114, v127
	v_mov_b32_e32 v113, v127
	v_mov_b32_e32 v112, v127
	v_mov_b32_e32 v103, v127
	v_mov_b32_e32 v102, v127
	v_mov_b32_e32 v101, v127
	v_mov_b32_e32 v100, v127
	v_mov_b32_e32 v99, v127
	v_mov_b32_e32 v98, v127
	v_mov_b32_e32 v97, v127
	v_mov_b32_e32 v96, v127
	v_mov_b32_e32 v87, v127
	v_mov_b32_e32 v86, v127
	v_mov_b32_e32 v85, v127
	v_mov_b32_e32 v84, v127
	v_mov_b32_e32 v83, v127
	v_mov_b32_e32 v82, v127
	v_mov_b32_e32 v81, v127
	v_mov_b32_e32 v80, v127
	v_mov_b32_e32 v71, v127
	v_mov_b32_e32 v70, v127
	v_mov_b32_e32 v69, v127
	v_mov_b32_e32 v68, v127
	v_mov_b32_e32 v67, v127
	v_mov_b32_e32 v66, v127
	v_mov_b32_e32 v65, v127
	v_mov_b32_e32 v64, v127
	v_mov_b32_e32 v63, v127
	v_mov_b32_e32 v62, v127
	v_mov_b32_e32 v61, v127
	v_mov_b32_e32 v60, v127
	v_mov_b32_e32 v59, v127
	v_mov_b32_e32 v58, v127
	v_mov_b32_e32 v57, v127
	v_mov_b32_e32 v56, v127
	v_mov_b32_e32 v47, v127
	v_mov_b32_e32 v46, v127
	v_mov_b32_e32 v45, v127
	v_mov_b32_e32 v44, v127
	v_mov_b32_e32 v43, v127
	v_mov_b32_e32 v42, v127
	v_mov_b32_e32 v41, v127
	v_mov_b32_e32 v40, v127
	v_mov_b32_e32 v31, v127
	v_mov_b32_e32 v30, v127
	v_mov_b32_e32 v29, v127
	v_mov_b32_e32 v28, v127
	v_mov_b32_e32 v27, v127
	v_mov_b32_e32 v26, v127
	v_mov_b32_e32 v25, v127
	v_mov_b32_e32 v24, v127
	v_mov_b32_e32 v15, v127
	v_mov_b32_e32 v14, v127
	v_mov_b32_e32 v13, v127
	v_mov_b32_e32 v12, v127
	v_mov_b32_e32 v11, v127
	v_mov_b32_e32 v10, v127
	v_mov_b32_e32 v9, v127
	v_mov_b32_e32 v8, v127
	v_mov_b32_e32 v55, v127
	v_mov_b32_e32 v54, v127
	v_mov_b32_e32 v53, v127
	v_mov_b32_e32 v52, v127
	v_mov_b32_e32 v51, v127
	v_mov_b32_e32 v50, v127
	v_mov_b32_e32 v49, v127
	v_mov_b32_e32 v48, v127
	v_mov_b32_e32 v39, v127
	v_mov_b32_e32 v38, v127
	v_mov_b32_e32 v37, v127
	v_mov_b32_e32 v36, v127
	v_mov_b32_e32 v35, v127
	v_mov_b32_e32 v34, v127
	v_mov_b32_e32 v33, v127
	v_mov_b32_e32 v32, v127
	v_mov_b32_e32 v23, v127
	v_mov_b32_e32 v22, v127
	v_mov_b32_e32 v21, v127
	v_mov_b32_e32 v20, v127
	v_mov_b32_e32 v19, v127
	v_mov_b32_e32 v18, v127
	v_mov_b32_e32 v17, v127
	v_mov_b32_e32 v16, v127
	v_mov_b32_e32 v7, v127
	v_mov_b32_e32 v6, v127
	v_mov_b32_e32 v5, v127
	v_mov_b32_e32 v4, v127
	v_mov_b32_e32 v3, v127
	v_mov_b32_e32 v2, v127
	v_mov_b32_e32 v1, v127
	v_mov_b32_e32 v0, v127
	s_cbranch_vccnz .LBB0_2424
	s_and_b64 s[10:11], s[10:11], exec
	s_cselect_b32 s21, s25, s31
	s_cselect_b32 s23, s24, s30
	s_cselect_b32 s62, s27, s29
	s_cselect_b32 s63, s26, s28
	s_add_u32 s10, s30, 0x10080
	s_addc_u32 s11, s31, 0
	s_add_u32 s64, s28, 0x100
	s_addc_u32 s65, s29, 0
	s_mov_b32 s28, 0

; #define PG8_STAGE(bufoff, gbase, voff) do { _Pragma("unroll") for (int _i = 0; _i < 2; ++_i) \
;         __builtin_amdgcn_global_load_lds((const unsigned*)((const char*)(gbase) + (voff)[_i]), (LAS unsigned*)(lds + (bufoff) + ldsw + _i * 8192), 16, 0, 0); } while (0)
; #define PG8_WAIT_V(n) asm volatile("s_waitcnt vmcnt(" #n ")" ::: "memory")
; #define PG8_BAR __builtin_amdgcn_s_barrier()
; template <class Epi>
; __device__ __forceinline__ void gemm_phase(LAS unsigned char* lds, const Gemm g, const StaticOrder& S, const Epi& E) {
;     ...
;     f32x4 acc[2][2][4][2];
; #pragma unroll
;     for (int a = 0; a < 2; ++a)
; #pragma unroll
;         for (int b = 0; b < 2; ++b)
; #pragma unroll
;             for (int m = 0; m < 4; ++m)
; #pragma unroll
;                 for (int n = 0; n < 2; ++n) acc[a][b][m][n] = (f32x4){0.f, 0.f, 0.f, 0.f};
;     bf16x8 At[4][2], B0[2][2], B1[2][2];
;     const char* cA = (const char*)g.A + (size_t)cur.pm * tstepA + (size_t)cur.pn * g.a_pn_off * 2; const char* cB = (const char*)g.Bt + (size_t)cur.pn * tstepB;
;     PG8_STAGE(PG8_SB(0, 0), cB, voffB); PG8_STAGE(PG8_SA(0, 0), cA, voffA); PG8_STAGE(PG8_SB(0, 1), cB + hstepB, voffB); PG8_STAGE(PG8_SA(0, 1), cA + hstepA, voffA);
;     if (wr == 1) PG8_BAR;
;     PG8_WAIT_V(4); PG8_BAR;
;     PG8_STAGE(PG8_SB(1, 0), cB + kstep, voffB); PG8_STAGE(PG8_SA(1, 0), cA + kstep, voffA); PG8_STAGE(PG8_SB(1, 1), cB + hstepB + kstep, voffB);
;     PG8_WAIT_V(6); PG8_BAR;
;     for (;;) {
;         const bool has_next = S.next(ui + 1, nxt);
;         const char* nA = has_next ? (const char*)g.A + (size_t)nxt.pm * tstepA + (size_t)nxt.pn * g.a_pn_off * 2 : cA; const char* nB = has_next ? (const char*)g.Bt + (size_t)nxt.pn * tstepB : cB;
;         for (int t = 0; t < nt; t += 2) {
;             const bool last = (t == nt - 2);
;             const char* a1 = cA + (size_t)(t + 1) * kstep;
;             const char* a2 = last ? nA : cA + (size_t)(t + 2) * kstep; const char* b2 = last ? nB : cB + (size_t)(t + 2) * kstep;
.LBB0_2618:
	s_ashr_i32 s27, s26, 31
	s_lshl_b64 s[28:29], s[26:27], 19
	s_add_u32 s28, s70, s28
	s_addc_u32 s29, s71, s29
	s_ashr_i32 s25, s24, 31
	s_lshl_b64 s[30:31], s[24:25], 19
	s_add_u32 s30, s18, s30
	v_mov_b32_e32 v127, 0
	v_cmp_lt_i64_e64 s[12:13], s[12:13], v[164:165]
	s_addc_u32 s31, s19, s31
	s_and_b64 vcc, exec, s[8:9]
	v_mov_b32_e32 v126, v127
	v_mov_b32_e32 v125, v127
	v_mov_b32_e32 v124, v127
	v_mov_b32_e32 v123, v127
	v_mov_b32_e32 v122, v127
	v_mov_b32_e32 v121, v127
	v_mov_b32_e32 v120, v127
	v_mov_b32_e32 v111, v127
	v_mov_b32_e32 v110, v127
	v_mov_b32_e32 v109, v127
	v_mov_b32_e32 v108, v127
	v_mov_b32_e32 v107, v127
	v_mov_b32_e32 v106, v127
	v_mov_b32_e32 v105, v127
	v_mov_b32_e32 v104, v127
	v_mov_b32_e32 v95, v127
	v_mov_b32_e32 v94, v127
	v_mov_b32_e32 v93, v127
	v_mov_b32_e32 v92, v127
	v_mov_b32_e32 v91, v127
	v_mov_b32_e32 v90, v127
	v_mov_b32_e32 v89, v127
	v_mov_b32_e32 v88, v127
	v_mov_b32_e32 v79, v127
	v_mov_b32_e32 v78, v127
	v_mov_b32_e32 v77, v127
	v_mov_b32_e32 v76, v127
	v_mov_b32_e32 v75, v127
	v_mov_b32_e32 v74, v127
	v_mov_b32_e32 v73, v127
	v_mov_b32_e32 v72, v127
	v_mov_b32_e32 v119, v127
	v_mov_b32_e32 v118, v127
	v_mov_b32_e32 v117, v127
	v_mov_b32_e32 v116, v127
	v_mov_b32_e32 v115, v127
	v_mov_b32_e32 v114, v127
	v_mov_b32_e32 v113, v127
	v_mov_b32_e32 v112, v127
	v_mov_b32_e32 v103, v127
	v_mov_b32_e32 v102, v127
	v_mov_b32_e32 v101, v127
	v_mov_b32_e32 v100, v127
	v_mov_b32_e32 v99, v127
	v_mov_b32_e32 v98, v127
	v_mov_b32_e32 v97, v127
	v_mov_b32_e32 v96, v127
	v_mov_b32_e32 v87, v127
	v_mov_b32_e32 v86, v127
	v_mov_b32_e32 v85, v127
	v_mov_b32_e32 v84, v127
	v_mov_b32_e32 v83, v127
	v_mov_b32_e32 v82, v127
	v_mov_b32_e32 v81, v127
	v_mov_b32_e32 v80, v127
	v_mov_b32_e32 v71, v127
	v_mov_b32_e32 v70, v127
	v_mov_b32_e32 v69, v127
	v_mov_b32_e32 v68, v127
	v_mov_b32_e32 v67, v127
	v_mov_b32_e32 v66, v127
	v_mov_b32_e32 v65, v127
	v_mov_b32_e32 v64, v127
	v_mov_b32_e32 v63, v127
	v_mov_b32_e32 v62, v127
	v_mov_b32_e32 v61, v127
	v_mov_b32_e32 v60, v127
	v_mov_b32_e32 v59, v127
	v_mov_b32_e32 v58, v127
	v_mov_b32_e32 v57, v127
	v_mov_b32_e32 v56, v127
	v_mov_b32_e32 v47, v127
	v_mov_b32_e32 v46, v127
	v_mov_b32_e32 v45, v127
	v_mov_b32_e32 v44, v127
	v_mov_b32_e32 v43, v127
	v_mov_b32_e32 v42, v127
	v_mov_b32_e32 v41, v127
	v_mov_b32_e32 v40, v127
	v_mov_b32_e32 v31, v127
	v_mov_b32_e32 v30, v127
	v_mov_b32_e32 v29, v127
	v_mov_b32_e32 v28, v127
	v_mov_b32_e32 v27, v127
	v_mov_b32_e32 v26, v127
	v_mov_b32_e32 v25, v127
	v_mov_b32_e32 v24, v127
	v_mov_b32_e32 v15, v127
	v_mov_b32_e32 v14, v127
	v_mov_b32_e32 v13, v127
	v_mov_b32_e32 v12, v127
	v_mov_b32_e32 v11, v127
	v_mov_b32_e32 v10, v127
	v_mov_b32_e32 v9, v127
	v_mov_b32_e32 v8, v127
	v_mov_b32_e32 v55, v127
	v_mov_b32_e32 v54, v127
	v_mov_b32_e32 v53, v127
	v_mov_b32_e32 v52, v127
	v_mov_b32_e32 v51, v127
	v_mov_b32_e32 v50, v127
	v_mov_b32_e32 v49, v127
	v_mov_b32_e32 v48, v127
	v_mov_b32_e32 v39, v127
	v_mov_b32_e32 v38, v127
	v_mov_b32_e32 v37, v127
	v_mov_b32_e32 v36, v127
	v_mov_b32_e32 v35, v127
	v_mov_b32_e32 v34, v127
	v_mov_b32_e32 v33, v127
	v_mov_b32_e32 v32, v127
	v_mov_b32_e32 v23, v127
	v_mov_b32_e32 v22, v127
	v_mov_b32_e32 v21, v127
	v_mov_b32_e32 v20, v127
	v_mov_b32_e32 v19, v127
	v_mov_b32_e32 v18, v127
	v_mov_b32_e32 v17, v127
	v_mov_b32_e32 v16, v127
	v_mov_b32_e32 v7, v127
	v_mov_b32_e32 v6, v127
	v_mov_b32_e32 v5, v127
	v_mov_b32_e32 v4, v127
	v_mov_b32_e32 v3, v127
	v_mov_b32_e32 v2, v127
	s_waitcnt lgkmcnt(0)
	v_mov_b32_e32 v1, v127
	v_mov_b32_e32 v0, v127
	s_cbranch_vccnz .LBB0_2621
	s_and_b64 s[12:13], s[12:13], exec
	s_cselect_b32 s25, s29, s41
	s_cselect_b32 s27, s28, s40
	s_cselect_b32 s64, s31, s39
	s_cselect_b32 s65, s30, s38
	s_add_u32 s12, s40, 0x40080
	s_addc_u32 s13, s41, 0
	s_add_u32 s76, s38, 0x100
	s_addc_u32 s77, s39, 0
	s_mov_b32 s38, 0
